# 40% of the late weight copies moved to the 64 workgroups idle in P1's last round; mLSTM inter-chunk product LDS reads pipelined
# baseline (speedup 1.0000x reference)
; #define LAS __attribute__((address_space(3)))
; __device__ __forceinline__ void p0_transposes(Frame& F, int it_lo, int it_hi, int gw, int NGW) {
;     int tx_ = (int)threadIdx.x; asm volatile("" : "+v"(tx_)); const int lane = tx_ & 63;
;     LAS float* scr = (LAS float*)(F.lds + RING_OFF + F.wave * 16384);
;     int it = it_lo + gw; if (it >= it_hi) return;
; template <int PH> __device__ __forceinline__ void run_phase(Frame& F, const Args& args) {
;     ...
;         if (F.G == 256 && blockIdx.x >= 192) p0_transposes(F, P0_I_W1, P0_I_W1 + P0_SPLIT, ((int)blockIdx.x - 192) * NWAVES + F.wave, 64 * NWAVES);
.LBB0_231:
	v_readlane_b32 s2, v241, 46
	s_cmpk_lt_u32 s96, 0xc0
	v_readlane_b32 s3, v241, 47
	s_cselect_b64 s[0:1], -1, 0
	s_xor_b64 s[2:3], s[2:3], -1
	s_or_b64 s[0:1], s[0:1], s[2:3]
	s_and_b64 vcc, exec, s[0:1]
	s_cbranch_vccnz .LBB0_233
	s_lshl_b32 s0, s96, 3
	v_readlane_b32 s1, v241, 48
	s_add_i32 s0, s0, s1
	s_addk_i32 s0, 0xfa00
	v_mov_b32_e32 v1, v0
	v_writelane_b32 v242, s0, 0
	v_writelane_b32 v242, s1, 1
	v_writelane_b32 v242, s2, 2
	v_writelane_b32 v242, s3, 3
	v_writelane_b32 v242, s4, 4
	v_writelane_b32 v242, s5, 5
	v_writelane_b32 v242, s6, 6
	v_writelane_b32 v242, s7, 7
	v_writelane_b32 v242, s8, 8
	v_writelane_b32 v242, s9, 9
	v_writelane_b32 v242, s10, 10
	v_writelane_b32 v242, s11, 11
	v_writelane_b32 v242, s12, 12
	v_writelane_b32 v242, s13, 13
	v_writelane_b32 v242, s14, 14
	v_writelane_b32 v242, s15, 15
	v_writelane_b32 v242, s16, 16
	v_writelane_b32 v242, s17, 17
	v_writelane_b32 v242, s18, 18
	v_writelane_b32 v242, s19, 19
	v_writelane_b32 v242, s20, 20
	v_writelane_b32 v242, s21, 21
	v_writelane_b32 v242, s22, 22
	v_writelane_b32 v242, s23, 23
	v_writelane_b32 v242, s24, 24
	v_writelane_b32 v242, s25, 25
	v_writelane_b32 v242, s26, 26
	v_writelane_b32 v242, s27, 27
	v_writelane_b32 v242, s28, 28
	v_writelane_b32 v242, s29, 29
	v_writelane_b32 v242, s30, 30
	v_writelane_b32 v242, s31, 31
	v_writelane_b32 v242, s32, 32
	v_writelane_b32 v242, s33, 33
	v_writelane_b32 v242, s34, 34
	v_writelane_b32 v242, s35, 35
	v_writelane_b32 v242, s36, 36
	v_writelane_b32 v242, s37, 37
	v_writelane_b32 v242, s38, 38
	v_writelane_b32 v242, s39, 39
	v_writelane_b32 v242, s40, 40
	v_writelane_b32 v242, s41, 41
	v_writelane_b32 v242, s42, 42
	v_writelane_b32 v242, s43, 43
	v_writelane_b32 v242, s44, 44
	v_writelane_b32 v242, s45, 45
	v_writelane_b32 v242, s46, 46
	v_writelane_b32 v242, s47, 47
	v_writelane_b32 v242, s48, 48
	v_writelane_b32 v242, s49, 49
	v_writelane_b32 v242, s50, 50
	v_writelane_b32 v242, s51, 51
	v_writelane_b32 v242, s52, 52
	v_writelane_b32 v242, s53, 53
	v_writelane_b32 v242, s54, 54
	v_writelane_b32 v242, s55, 55
	v_writelane_b32 v242, s56, 56
	v_writelane_b32 v242, s57, 57
	v_writelane_b32 v242, s58, 58
	v_writelane_b32 v242, s59, 59
	v_writelane_b32 v242, s60, 60
	v_writelane_b32 v242, s61, 61
	v_writelane_b32 v242, s62, 62
	v_writelane_b32 v242, s63, 63
	v_writelane_b32 v243, s64, 0
	v_writelane_b32 v243, s65, 1
	v_writelane_b32 v243, s66, 2
	v_writelane_b32 v243, s67, 3
	v_writelane_b32 v243, s68, 4
	v_writelane_b32 v243, s69, 5
	v_writelane_b32 v243, s70, 6
	v_writelane_b32 v243, s71, 7
	v_writelane_b32 v243, s72, 8
	v_writelane_b32 v243, s73, 9
	v_writelane_b32 v243, s74, 10
	v_writelane_b32 v243, s75, 11
	v_writelane_b32 v243, s76, 12
	v_writelane_b32 v243, s77, 13
	v_writelane_b32 v243, s78, 14
	v_writelane_b32 v243, s79, 15
	v_writelane_b32 v243, s80, 16
	v_writelane_b32 v243, s81, 17
	v_writelane_b32 v243, s82, 18
	v_writelane_b32 v243, s83, 19
	v_writelane_b32 v243, s84, 20
	v_writelane_b32 v243, s85, 21
	v_writelane_b32 v243, s86, 22
	v_writelane_b32 v243, s87, 23
	v_writelane_b32 v243, s88, 24
	v_writelane_b32 v243, s89, 25
	v_writelane_b32 v243, s90, 26
	v_writelane_b32 v243, s91, 27
	v_writelane_b32 v243, s92, 28
	v_writelane_b32 v243, s93, 29
	v_writelane_b32 v243, s94, 30
	v_writelane_b32 v243, s95, 31
	v_writelane_b32 v243, s96, 32
	v_writelane_b32 v243, s97, 33
	v_writelane_b32 v243, vcc_lo, 34
	v_writelane_b32 v243, vcc_hi, 35
	v_mov_b32_e32 v244, v1
	v_mov_b32_e32 v245, v2
	v_mov_b32_e32 v246, v3
	v_mov_b32_e32 v247, v4
	v_mov_b32_e32 v248, v5
	v_mov_b32_e32 v249, v7
	v_mov_b32_e32 v250, v10
	v_mov_b32_e32 v251, v14
	v_mov_b32_e32 v252, v15
	s_mov_b32 s12, s0
	s_movk_i32 s101, 0xd80
	v_readlane_b32 s68, v241, 42
	v_readlane_b32 s69, v241, 43
	v_writelane_b32 v241, s94, 55
	v_writelane_b32 v241, s95, 56
	s_or_b32 s99, s99, 1
	s_branch .Ltr_entry
; __device__ __forceinline__ void p0_transposes(Frame& F, int it_lo, int it_hi, int gw, int NGW) {
;     ...
;     for (;;) {
;         const int nx = it + NGW; const bool more = nx < it_hi;
;         TrItem nxt = cur; f32x4 v2[8]; float g2[8];
;         if (more) { nxt = tr_decode(F, nx); tr_load(nxt, v2, g2, lane); }
;         tr_store(cur, v, g, scr, lane);
;         if (!more) break;
;         cur = nxt; it = nx;
; #pragma unroll
;         for (int i = 0; i < 8; ++i) { v[i] = v2[i]; g[i] = g2[i]; }
;     }
; }
; template <int PH> __device__ __forceinline__ void run_phase(Frame& F, const Args& args) {
;     ...
;         if (F.G == 256 && blockIdx.x >= 192) p0_transposes(F, P0_I_W1, P0_I_W1 + P0_SPLIT, ((int)blockIdx.x - 192) * NWAVES + F.wave, 64 * NWAVES);
.Lp1_ret:
	s_bitcmp1_b32 s99, 1
	s_cbranch_scc1 .Lp1_done
	s_or_b32 s99, s99, 2
	v_readlane_b32 s12, v242, 0
	s_nop 3
	s_addk_i32 s12, 0x200
	v_mov_b32_e32 v1, v0
	s_branch .Ltr_entry
.Lp1_done:
	s_and_b32 s99, s99, 0xfffffffc
	v_mov_b32_e32 v1, v244
	v_mov_b32_e32 v2, v245
	v_mov_b32_e32 v3, v246
	v_mov_b32_e32 v4, v247
	v_mov_b32_e32 v5, v248
	v_mov_b32_e32 v7, v249
	v_mov_b32_e32 v10, v250
	v_mov_b32_e32 v14, v251
	v_mov_b32_e32 v15, v252
	v_readlane_b32 s0, v242, 0
	v_readlane_b32 s1, v242, 1
	v_readlane_b32 s2, v242, 2
	v_readlane_b32 s3, v242, 3
	v_readlane_b32 s4, v242, 4
	v_readlane_b32 s5, v242, 5
	v_readlane_b32 s6, v242, 6
	v_readlane_b32 s7, v242, 7
	v_readlane_b32 s8, v242, 8
	v_readlane_b32 s9, v242, 9
	v_readlane_b32 s10, v242, 10
	v_readlane_b32 s11, v242, 11
	v_readlane_b32 s12, v242, 12
	v_readlane_b32 s13, v242, 13
	v_readlane_b32 s14, v242, 14
	v_readlane_b32 s15, v242, 15
	v_readlane_b32 s16, v242, 16
	v_readlane_b32 s17, v242, 17
	v_readlane_b32 s18, v242, 18
	v_readlane_b32 s19, v242, 19
	v_readlane_b32 s20, v242, 20
	v_readlane_b32 s21, v242, 21
	v_readlane_b32 s22, v242, 22
	v_readlane_b32 s23, v242, 23
	v_readlane_b32 s24, v242, 24
	v_readlane_b32 s25, v242, 25
	v_readlane_b32 s26, v242, 26
	v_readlane_b32 s27, v242, 27
	v_readlane_b32 s28, v242, 28
	v_readlane_b32 s29, v242, 29
	v_readlane_b32 s30, v242, 30
	v_readlane_b32 s31, v242, 31
	v_readlane_b32 s32, v242, 32
	v_readlane_b32 s33, v242, 33
	v_readlane_b32 s34, v242, 34
	v_readlane_b32 s35, v242, 35
	v_readlane_b32 s36, v242, 36
	v_readlane_b32 s37, v242, 37
	v_readlane_b32 s38, v242, 38
	v_readlane_b32 s39, v242, 39
	v_readlane_b32 s40, v242, 40
	v_readlane_b32 s41, v242, 41
	v_readlane_b32 s42, v242, 42
	v_readlane_b32 s43, v242, 43
	v_readlane_b32 s44, v242, 44
	v_readlane_b32 s45, v242, 45
	v_readlane_b32 s46, v242, 46
	v_readlane_b32 s47, v242, 47
	v_readlane_b32 s48, v242, 48
	v_readlane_b32 s49, v242, 49
	v_readlane_b32 s50, v242, 50
	v_readlane_b32 s51, v242, 51
	v_readlane_b32 s52, v242, 52
	v_readlane_b32 s53, v242, 53
	v_readlane_b32 s54, v242, 54
	v_readlane_b32 s55, v242, 55
	v_readlane_b32 s56, v242, 56
	v_readlane_b32 s57, v242, 57
	v_readlane_b32 s58, v242, 58
	v_readlane_b32 s59, v242, 59
	v_readlane_b32 s60, v242, 60
	v_readlane_b32 s61, v242, 61
	v_readlane_b32 s62, v242, 62
	v_readlane_b32 s63, v242, 63
	v_readlane_b32 s64, v243, 0
	v_readlane_b32 s65, v243, 1
	v_readlane_b32 s66, v243, 2
	v_readlane_b32 s67, v243, 3
	v_readlane_b32 s68, v243, 4
	v_readlane_b32 s69, v243, 5
	v_readlane_b32 s70, v243, 6
	v_readlane_b32 s71, v243, 7
	v_readlane_b32 s72, v243, 8
	v_readlane_b32 s73, v243, 9
	v_readlane_b32 s74, v243, 10
	v_readlane_b32 s75, v243, 11
	v_readlane_b32 s76, v243, 12
	v_readlane_b32 s77, v243, 13
	v_readlane_b32 s78, v243, 14
	v_readlane_b32 s79, v243, 15
	v_readlane_b32 s80, v243, 16
	v_readlane_b32 s81, v243, 17
	v_readlane_b32 s82, v243, 18
	v_readlane_b32 s83, v243, 19
	v_readlane_b32 s84, v243, 20
	v_readlane_b32 s85, v243, 21
	v_readlane_b32 s86, v243, 22
	v_readlane_b32 s87, v243, 23
	v_readlane_b32 s88, v243, 24
	v_readlane_b32 s89, v243, 25
	v_readlane_b32 s90, v243, 26
	v_readlane_b32 s91, v243, 27
	v_readlane_b32 s92, v243, 28
	v_readlane_b32 s93, v243, 29
	v_readlane_b32 s94, v243, 30
	v_readlane_b32 s95, v243, 31
	v_readlane_b32 s96, v243, 32
	v_readlane_b32 s97, v243, 33
	v_readlane_b32 vcc_lo, v243, 34
	v_readlane_b32 vcc_hi, v243, 35
	s_nop 7

; #define LAS __attribute__((address_space(3)))
; __device__ __forceinline__ float fexp(float x) { return __builtin_amdgcn_exp2f(x * LOG2E); }
; __device__ __forceinline__ float bflo(unsigned w) { return __uint_as_float(w << 16); }
; __device__ __forceinline__ float bfhi(unsigned w) { return __uint_as_float(w & 0xffff0000u); }
; __device__ __forceinline__ void ml_out_unit(LAS unsigned char* lds, const MixBufs& B, int b, int h, int seg, int tid) {
;     ...
;             const float fct = FC[16 * ti + c];
;             float mx = -INFINITY;
; #pragma unroll
;             for (int s4 = 0; s4 < 4; ++s4) { const f32x4 l4 = *(const LAS f32x4*)(LI + 16 * g + 4 * s4), f4 = *(const LAS f32x4*)(FC + 16 * g + 4 * s4);
; #pragma unroll
;                 for (int e = 0; e < 4; ++e) mx = fmaxf(mx, l4[e] - fabsf(fct - f4[e])); }
;             mx = fmaxf(mx, __shfl_xor(mx, 16)); mx = fmaxf(mx, __shfl_xor(mx, 32));
;             const float gi = fct + m, mt = fmaxf(gi, mx), sc = fexp(gi - mt);
;             bf16x8 qf[4];
; #pragma unroll
;             for (int kk = 0; kk < 4; ++kk) qf[kk] = frag_row(lds + O_Q, GP128, 16 * ti, 32 * kk, lane);
;             float qn = 0.f;
; #pragma unroll
;             for (int kk = 0; kk < 4; ++kk) { const v4u qq = __builtin_bit_cast(v4u, qf[kk]); const f32x4 n0 = *(const LAS f32x4*)(NVc + 32 * kk + 8 * g), n1 = *(const LAS f32x4*)(NVc + 32 * kk + 8 * g + 4);
;                 qn += (bflo(qq.x) * n0[0] + bfhi(qq.x) * n0[1]) + (bflo(qq.y) * n0[2] + bfhi(qq.y) * n0[3]) + (bflo(qq.z) * n1[0] + bfhi(qq.z) * n1[1]) + (bflo(qq.w) * n1[2] + bfhi(qq.w) * n1[3]); }
;             qn += __shfl_xor(qn, 16); qn += __shfl_xor(qn, 32);
.LBB0_672:
	v_add_f32_e32 v2, v186, v12
	v_max_f32_e32 v12, v13, v13
	v_max_f32_e32 v198, v2, v12
	s_waitcnt lgkmcnt(0)
	s_barrier
	ds_read_b32 v2, v157
	ds_read_b128 v[12:15], v159
	ds_read_b128 v[16:19], v159 offset:16
	ds_read_b128 v[20:23], v159 offset:32
	ds_read_b128 v[24:27], v159 offset:48
	ds_read_b128 v[28:31], v160
	ds_read_b128 v[32:35], v160 offset:16
	ds_read_b128 v[36:39], v160 offset:32
	ds_read_b128 v[40:43], v160 offset:48
	s_mov_b32 s5, 0xff800000
	s_waitcnt lgkmcnt(3)
	v_sub_f32_e32 v28, v2, v28
	v_sub_f32_e64 v12, v12, |v28|
	v_sub_f32_e32 v28, v2, v29
	v_sub_f32_e64 v13, v13, |v28|
	v_max3_f32 v12, v12, s5, v13
	v_sub_f32_e32 v13, v2, v30
	v_sub_f32_e64 v13, v14, |v13|
	v_sub_f32_e32 v14, v2, v31
	v_sub_f32_e64 v14, v15, |v14|
	v_max3_f32 v12, v12, v13, v14
	s_waitcnt lgkmcnt(2)
	v_sub_f32_e32 v13, v2, v32
	v_sub_f32_e32 v14, v2, v33
	v_sub_f32_e64 v13, v16, |v13|
	v_sub_f32_e64 v14, v17, |v14|
	v_max3_f32 v12, v12, v13, v14
	v_sub_f32_e32 v13, v2, v34
	v_sub_f32_e32 v14, v2, v35
	v_sub_f32_e64 v13, v18, |v13|
	v_sub_f32_e64 v14, v19, |v14|
	v_max3_f32 v12, v12, v13, v14
	s_waitcnt lgkmcnt(1)
	v_sub_f32_e32 v13, v2, v36
	v_sub_f32_e32 v14, v2, v37
	v_sub_f32_e64 v13, v20, |v13|
	v_sub_f32_e64 v14, v21, |v14|
	v_max3_f32 v12, v12, v13, v14
	v_sub_f32_e32 v13, v2, v38
	v_sub_f32_e32 v14, v2, v39
	v_sub_f32_e64 v13, v22, |v13|
	v_sub_f32_e64 v14, v23, |v14|
	v_max3_f32 v12, v12, v13, v14
	s_waitcnt lgkmcnt(0)
	v_sub_f32_e32 v13, v2, v40
	v_sub_f32_e32 v14, v2, v41
	v_sub_f32_e64 v13, v24, |v13|
	v_sub_f32_e64 v14, v25, |v14|
	v_max3_f32 v12, v12, v13, v14
	v_sub_f32_e32 v13, v2, v42
	v_sub_f32_e32 v14, v2, v43
	v_sub_f32_e64 v13, v26, |v13|
	v_sub_f32_e64 v14, v27, |v14|
	v_max3_f32 v12, v12, v13, v14
	v_and_b32_e32 v14, 64, v183
	v_xor_b32_e32 v13, 16, v183
	v_add_u32_e32 v14, 64, v14
	v_cmp_lt_i32_e32 vcc, v13, v14
	s_cmp_eq_u32 s7, 0
	s_cselect_b32 s5, 0x22000, s97
	v_cndmask_b32_e32 v13, v183, v13, vcc
	v_lshlrev_b32_e32 v200, 2, v13
	ds_bpermute_b32 v13, v200, v12
	v_add_u32_e32 v47, s5, v163
	s_cselect_b32 s4, 0x11000, s96
	s_waitcnt lgkmcnt(0)
	v_max_f32_e32 v13, v13, v13
	v_max_f32_e32 v12, v12, v13
	v_xor_b32_e32 v13, 32, v183
	v_cmp_lt_i32_e32 vcc, v13, v14
	v_add_f32_e32 v14, v186, v2
	s_nop 0
	v_cndmask_b32_e32 v13, v183, v13, vcc
	v_lshlrev_b32_e32 v199, 2, v13
	ds_bpermute_b32 v13, v199, v12
	s_waitcnt lgkmcnt(0)
	v_max3_f32 v102, v14, v12, v13
	v_sub_f32_e32 v12, v14, v102
	v_mul_f32_e32 v46, 0x3fb8aa3b, v12
	v_add_u32_e32 v12, v161, v158
	ds_read_b128 v[24:27], v12
	ds_read_b128 v[20:23], v12 offset:64
	ds_read_b128 v[16:19], v12 offset:128
	ds_read_b128 v[12:15], v12 offset:192
	ds_read_b128 v[28:31], v47
	ds_read_b128 v[32:35], v47 offset:16
	s_waitcnt lgkmcnt(5)
	v_lshlrev_b32_e32 v40, 16, v24
	v_and_b32_e32 v41, 0xffff0000, v25
	v_and_b32_e32 v36, 0xffff0000, v24
	s_waitcnt lgkmcnt(1)
	v_mov_b32_e32 v38, v29
	v_mov_b32_e32 v29, v31
	v_lshlrev_b32_e32 v37, 16, v25
	v_mov_b32_e32 v39, v30
	v_pk_mul_f32 v[28:29], v[28:29], v[40:41]
	v_and_b32_e32 v41, 0xffff0000, v21
	v_pk_fma_f32 v[44:45], v[38:39], v[36:37], v[28:29]
	ds_read_b128 v[28:31], v47 offset:128
	ds_read_b128 v[36:39], v47 offset:144
	v_lshlrev_b32_e32 v40, 16, v21
	v_and_b32_e32 v51, 0xffff0000, v20
	v_and_b32_e32 v50, 0xffff0000, v22
	s_waitcnt lgkmcnt(1)
	v_mul_f32_e32 v42, v31, v41
	v_pk_fma_f32 v[30:31], v[30:31], v[40:41], v[42:43] op_sel_hi:[1,1,0]
	v_mov_b32_e32 v43, v28
	s_waitcnt lgkmcnt(0)
	v_mov_b32_e32 v28, v37
	v_lshlrev_b32_e32 v41, 16, v20
	v_lshlrev_b32_e32 v40, 16, v22
	v_mov_b32_e32 v42, v36
	v_pk_mul_f32 v[28:29], v[28:29], v[50:51]
	v_and_b32_e32 v49, 0xffff0000, v26
	v_pk_fma_f32 v[28:29], v[42:43], v[40:41], v[28:29]
	v_lshlrev_b32_e32 v48, 16, v26
	v_pk_add_f32 v[30:31], v[28:29], v[30:31] op_sel:[1,0] op_sel_hi:[0,1]
	v_pk_add_f32 v[36:37], v[28:29], v[30:31]
	ds_read_b128 v[28:31], v47 offset:256
	ds_read_b128 v[40:43], v47 offset:272
	v_lshlrev_b32_e32 v37, 16, v17
	v_and_b32_e32 v51, 0xffff0000, v23
	v_lshlrev_b32_e32 v50, 16, v23
	s_waitcnt lgkmcnt(1)
	v_mul_f32_e32 v70, v30, v37
	v_and_b32_e32 v30, 0xffff0000, v17
	v_mul_f32_e32 v71, v31, v30
	v_lshlrev_b32_e32 v30, 16, v18
	v_and_b32_e32 v31, 0xffff0000, v18
	s_waitcnt lgkmcnt(0)
	v_mul_f32_e32 v68, v40, v30
	v_pk_fma_f32 v[30:31], v[40:41], v[30:31], v[68:69] op_sel_hi:[1,1,0]
	v_pk_mov_b32 v[40:41], v[26:27], v[16:17] op_sel:[1,0]
	v_lshlrev_b32_e32 v30, 16, v19
	v_mul_f32_e32 v72, v42, v30
	v_and_b32_e32 v30, 0xffff0000, v19
	v_mul_f32_e32 v37, v43, v30
	v_mul_f32_e32 v30, v33, v49
	v_mov_b32_e32 v68, v34
	v_mov_b32_e32 v69, v28
	v_and_b32_e32 v41, 0xffff0000, v41
	v_and_b32_e32 v40, 0xffff0000, v40
	v_mov_b32_e32 v28, v35
	v_pk_fma_f32 v[32:33], v[32:33], v[48:49], v[30:31] op_sel_hi:[1,1,0]
	v_pk_add_f32 v[34:35], v[44:45], v[44:45] op_sel:[0,1] op_sel_hi:[1,0]
	v_lshlrev_b32_e32 v43, 16, v16
	v_lshlrev_b32_e32 v42, 16, v27
	v_pk_mul_f32 v[28:29], v[28:29], v[40:41]
	v_mov_b32_e32 v33, v70
	v_mov_b32_e32 v35, v71
	v_pk_fma_f32 v[28:29], v[68:69], v[42:43], v[28:29]
	v_pk_add_f32 v[32:33], v[32:33], v[34:35]
	v_mov_b32_e32 v30, v3
	v_pk_add_f32 v[28:29], v[28:29], v[32:33]
	s_nop 0
	v_pk_add_f32 v[28:29], v[28:29], v[30:31]
	v_mul_f32_e32 v30, v39, v51
	v_pk_fma_f32 v[30:31], v[38:39], v[50:51], v[30:31] op_sel_hi:[1,1,0]
	s_nop 0
	v_mov_b32_e32 v31, v72
	v_pk_add_f32 v[30:31], v[30:31], v[36:37]
	v_lshlrev_b32_e32 v36, 16, v12
	v_pk_add_f32 v[28:29], v[30:31], v[28:29]
	s_nop 0
	v_pk_add_f32 v[68:69], v[28:29], v[28:29] op_sel:[0,1] op_sel_hi:[1,0]
	ds_read_b128 v[28:31], v47 offset:384
	ds_read_b128 v[32:35], v47 offset:400
	s_waitcnt lgkmcnt(1)
; #define LAS __attribute__((address_space(3)))
; #define MFMA16(a, b, c) __builtin_amdgcn_mfma_f32_16x16x32_bf16((a), (b), (c), 0, 0, 0)
; __device__ __forceinline__ float fexp(float x) { return __builtin_amdgcn_exp2f(x * LOG2E); }
; __device__ __forceinline__ float bflo(unsigned w) { return __uint_as_float(w << 16); }
; __device__ __forceinline__ float bfhi(unsigned w) { return __uint_as_float(w & 0xffff0000u); }
; __device__ __forceinline__ unsigned cvtpk(float lo, float hi) { const f32x2_t v = {lo, hi}; const bf16x2_t b = __builtin_convertvector(v, bf16x2_t); return __builtin_bit_cast(unsigned, b); }
; __device__ __forceinline__ void ml_out_unit(LAS unsigned char* lds, const MixBufs& B, int b, int h, int seg, int tid) {
;     ...
;             for (int kk = 0; kk < 4; ++kk) { const v4u qq = __builtin_bit_cast(v4u, qf[kk]); const f32x4 n0 = *(const LAS f32x4*)(NVc + 32 * kk + 8 * g), n1 = *(const LAS f32x4*)(NVc + 32 * kk + 8 * g + 4);
;                 qn += (bflo(qq.x) * n0[0] + bfhi(qq.x) * n0[1]) + (bflo(qq.y) * n0[2] + bfhi(qq.y) * n0[3]) + (bflo(qq.z) * n1[0] + bfhi(qq.z) * n1[1]) + (bflo(qq.w) * n1[2] + bfhi(qq.w) * n1[3]); }
;             qn += __shfl_xor(qn, 16); qn += __shfl_xor(qn, 32);
;             float dsum = 0.f; bf16x8 pb[2];
; #pragma unroll
;             for (int ks = 0; ks < 2; ++ks) { f32x4 p2[2];
; #pragma unroll
;                 for (int jj = 0; jj < 2; ++jj) { const int sj = 2 * ks + jj;
;                     f32x4 acc = (f32x4){0.f, 0.f, 0.f, 0.f};
; #pragma unroll
;                     for (int kk = 0; kk < 4; ++kk) acc = MFMA16(frag_row(lds + O_K, GP128, 16 * sj, 32 * kk, lane), qf[kk], acc);
;                     const f32x4 li4 = *(const LAS f32x4*)(LI + 16 * sj + 4 * g), fc4 = *(const LAS f32x4*)(FC + 16 * sj + 4 * g);
; #pragma unroll
;                     for (int i = 0; i < 4; ++i) { p2[jj][i] = acc[i] * fexp(li4[i] - fabsf(fct - fc4[i]) - mt); dsum += p2[jj][i]; } }
;                 v4u pk; pk.x = cvtpk(p2[0][0], p2[0][1]); pk.y = cvtpk(p2[0][2], p2[0][3]); pk.z = cvtpk(p2[1][0], p2[1][1]); pk.w = cvtpk(p2[1][2], p2[1][3]);
;                 pb[ks] = __builtin_bit_cast(bf16x8, pk); }
	v_mul_f32_e32 v72, v28, v36
	v_and_b32_e32 v28, 0xffff0000, v12
	v_mul_f32_e32 v78, v29, v28
	v_and_b32_e32 v29, 0xffff0000, v13
	v_lshlrev_b32_e32 v28, 16, v13
	v_mul_f32_e32 v36, v31, v29
	v_pk_fma_f32 v[76:77], v[30:31], v[28:29], v[36:37] op_sel_hi:[1,1,0]
	v_and_b32_e32 v29, 0xffff0000, v14
	v_lshlrev_b32_e32 v28, 16, v14
	s_waitcnt lgkmcnt(0)
	v_mul_f32_e32 v30, v33, v29
	v_pk_fma_f32 v[74:75], v[32:33], v[28:29], v[30:31] op_sel_hi:[1,1,0]
	v_and_b32_e32 v29, 0xffff0000, v15
	v_lshlrev_b32_e32 v28, 16, v15
	v_mul_f32_e32 v30, v35, v29
	v_pk_fma_f32 v[70:71], v[34:35], v[28:29], v[30:31] op_sel_hi:[1,1,0]
	ds_read_b128 v[28:31], v170 offset:17408
	ds_read_b128 v[32:35], v170 offset:17472
	s_waitcnt lgkmcnt(1)
	v_mfma_f32_16x16x32_bf16 v[28:31], v[28:31], v[24:27], 0
	s_waitcnt lgkmcnt(0)
	v_mfma_f32_16x16x32_bf16 v[28:31], v[32:35], v[20:23], v[28:31]
	ds_read_b128 v[32:35], v170 offset:17536
	s_waitcnt lgkmcnt(0)
	v_mfma_f32_16x16x32_bf16 v[28:31], v[32:35], v[16:19], v[28:31]
	ds_read_b128 v[32:35], v170 offset:17600
	s_waitcnt lgkmcnt(0)
	v_mfma_f32_16x16x32_bf16 v[28:31], v[32:35], v[12:15], v[28:31]
	ds_read_b128 v[32:35], v164
	ds_read_b128 v[36:39], v165
	s_waitcnt lgkmcnt(0)
	v_sub_f32_e32 v36, v2, v36
	v_sub_f32_e64 v32, v32, |v36|
	v_sub_f32_e32 v36, v2, v37
	v_sub_f32_e64 v33, v33, |v36|
	v_sub_f32_e32 v32, v32, v102
	v_sub_f32_e32 v33, v33, v102
	v_mul_f32_e32 v32, 0x3fb8aa3b, v32
	v_mul_f32_e32 v33, 0x3fb8aa3b, v33
	v_exp_f32_e32 v32, v32
	v_exp_f32_e32 v33, v33
	s_nop 0
	v_pk_mul_f32 v[40:41], v[28:29], v[32:33]
	s_nop 0
	v_add_f32_e32 v28, 0, v40
	v_add_f32_e32 v32, v41, v28
	v_sub_f32_e32 v28, v2, v38
	v_sub_f32_e32 v29, v2, v39
	v_sub_f32_e64 v28, v34, |v28|
	v_sub_f32_e64 v29, v35, |v29|
	v_sub_f32_e32 v28, v28, v102
	v_sub_f32_e32 v29, v29, v102
	v_mul_f32_e32 v28, 0x3fb8aa3b, v28
	v_mul_f32_e32 v29, 0x3fb8aa3b, v29
	v_exp_f32_e32 v28, v28
	v_exp_f32_e32 v29, v29
	s_nop 0
	v_pk_mul_f32 v[42:43], v[30:31], v[28:29]
	s_nop 0
	v_add_f32_e32 v28, v42, v32
	v_add_f32_e32 v44, v43, v28
	ds_read_b128 v[28:31], v170 offset:21760
	ds_read_b128 v[32:35], v170 offset:21824
	s_waitcnt lgkmcnt(1)
	v_mfma_f32_16x16x32_bf16 v[28:31], v[28:31], v[24:27], 0
	s_waitcnt lgkmcnt(0)
	v_mfma_f32_16x16x32_bf16 v[28:31], v[32:35], v[20:23], v[28:31]
	ds_read_b128 v[32:35], v170 offset:21888
	s_waitcnt lgkmcnt(0)
	v_mfma_f32_16x16x32_bf16 v[28:31], v[32:35], v[16:19], v[28:31]
	ds_read_b128 v[32:35], v170 offset:21952
	s_waitcnt lgkmcnt(0)
	v_mfma_f32_16x16x32_bf16 v[28:31], v[32:35], v[12:15], v[28:31]
	ds_read_b128 v[32:35], v164 offset:64
	ds_read_b128 v[36:39], v165 offset:64
	s_waitcnt lgkmcnt(0)
	v_sub_f32_e32 v36, v2, v36
	v_sub_f32_e64 v32, v32, |v36|
	v_sub_f32_e32 v36, v2, v37
	v_sub_f32_e64 v33, v33, |v36|
	v_sub_f32_e32 v32, v32, v102
	v_sub_f32_e32 v33, v33, v102
	v_mul_f32_e32 v32, 0x3fb8aa3b, v32
	v_mul_f32_e32 v33, 0x3fb8aa3b, v33
	v_exp_f32_e32 v32, v32
	v_exp_f32_e32 v33, v33
	s_nop 0
	v_pk_mul_f32 v[32:33], v[28:29], v[32:33]
	s_nop 0
	v_add_f32_e32 v28, v44, v32
	v_add_f32_e32 v36, v33, v28
	v_sub_f32_e32 v28, v2, v38
	v_sub_f32_e32 v29, v2, v39
	v_sub_f32_e64 v28, v34, |v28|
	v_sub_f32_e64 v29, v35, |v29|
	v_sub_f32_e32 v28, v28, v102
	v_sub_f32_e32 v29, v29, v102
	v_mul_f32_e32 v28, 0x3fb8aa3b, v28
	v_mul_f32_e32 v29, 0x3fb8aa3b, v29
	v_exp_f32_e32 v28, v28
	v_exp_f32_e32 v29, v29
	s_nop 0
	v_pk_mul_f32 v[34:35], v[30:31], v[28:29]
	s_nop 0
	v_add_f32_e32 v28, v34, v36
	v_add_f32_e32 v47, v35, v28
	v_cvt_pk_bf16_f32 v30, v32, v33
	v_cvt_pk_bf16_f32 v31, v34, v35
	ds_read_b128 v[32:35], v170 offset:26112
	ds_read_b128 v[36:39], v170 offset:26176
	s_waitcnt lgkmcnt(1)
	v_mfma_f32_16x16x32_bf16 v[32:35], v[32:35], v[24:27], 0
	v_cvt_pk_bf16_f32 v28, v40, v41
	v_cvt_pk_bf16_f32 v29, v42, v43
	s_waitcnt lgkmcnt(0)
	v_mfma_f32_16x16x32_bf16 v[32:35], v[36:39], v[20:23], v[32:35]
	ds_read_b128 v[36:39], v170 offset:26240
	s_waitcnt lgkmcnt(0)
	v_mfma_f32_16x16x32_bf16 v[32:35], v[36:39], v[16:19], v[32:35]
	ds_read_b128 v[36:39], v170 offset:26304
	s_waitcnt lgkmcnt(0)
	v_mfma_f32_16x16x32_bf16 v[32:35], v[36:39], v[12:15], v[32:35]
	ds_read_b128 v[36:39], v164 offset:128
	ds_read_b128 v[40:43], v165 offset:128
	s_waitcnt lgkmcnt(0)
	v_sub_f32_e32 v40, v2, v40
	v_sub_f32_e64 v36, v36, |v40|
	v_sub_f32_e32 v40, v2, v41
	v_sub_f32_e64 v37, v37, |v40|
	v_sub_f32_e32 v36, v36, v102
	v_sub_f32_e32 v37, v37, v102
	v_mul_f32_e32 v36, 0x3fb8aa3b, v36
	v_mul_f32_e32 v37, 0x3fb8aa3b, v37
	v_exp_f32_e32 v36, v36
	v_exp_f32_e32 v37, v37
	s_nop 0
	v_pk_mul_f32 v[44:45], v[32:33], v[36:37]
	s_nop 0
	v_add_f32_e32 v32, v47, v44
	v_add_f32_e32 v36, v45, v32
	v_sub_f32_e32 v32, v2, v42
	v_sub_f32_e32 v33, v2, v43
	v_sub_f32_e64 v32, v38, |v32|
	v_sub_f32_e64 v33, v39, |v33|
	v_sub_f32_e32 v32, v32, v102
	v_sub_f32_e32 v33, v33, v102
	v_mul_f32_e32 v32, 0x3fb8aa3b, v32
	v_mul_f32_e32 v33, 0x3fb8aa3b, v33
	v_exp_f32_e32 v32, v32
	v_exp_f32_e32 v33, v33
	s_nop 0
	v_pk_mul_f32 v[80:81], v[34:35], v[32:33]
	ds_read_b128 v[32:35], v170 offset:30464
	v_add_f32_e32 v79, v80, v36
	ds_read_b128 v[36:39], v170 offset:30528
	s_waitcnt lgkmcnt(1)
	v_mfma_f32_16x16x32_bf16 v[32:35], v[32:35], v[24:27], 0
	s_waitcnt lgkmcnt(0)
	v_mfma_f32_16x16x32_bf16 v[32:35], v[36:39], v[20:23], v[32:35]
	ds_read_b128 v[36:39], v170 offset:30592
	s_waitcnt lgkmcnt(0)
	v_mfma_f32_16x16x32_bf16 v[32:35], v[36:39], v[16:19], v[32:35]
	ds_read_b128 v[36:39], v170 offset:30656
	s_waitcnt lgkmcnt(0)
	v_mfma_f32_16x16x32_bf16 v[32:35], v[36:39], v[12:15], v[32:35]
	ds_read_b128 v[36:39], v164 offset:192
	ds_read_b128 v[40:43], v165 offset:192
	s_waitcnt lgkmcnt(0)
; #define GAS __attribute__((address_space(1)))
; #define MFMA16(a, b, c) __builtin_amdgcn_mfma_f32_16x16x32_bf16((a), (b), (c), 0, 0, 0)
; __device__ __forceinline__ void ml_out_unit(LAS unsigned char* lds, const MixBufs& B, int b, int h, int seg, int tid) {
;     ...
;             for (int vt = 0; vt < 8; ++vt) opv[vt] = *(const GAS u32x2*)(B.PROJ + trow * NPROJ + PC_OP + h * 128 + 16 * vt + 4 * g);
;             f32x4 a1[8];
; #pragma unroll
;             for (int hv = 0; hv < 2; ++hv) {
;                 f32x4 a2[4];
; #pragma unroll
;                 for (int j = 0; j < 4; ++j) a2[j] = (f32x4){0.f, 0.f, 0.f, 0.f};
; #pragma unroll
;                 for (int kk = 0; kk < 4; ++kk)
; #pragma unroll
;                     for (int j = 0; j < 4; ++j) a2[j] = MFMA16(frag_row(CTc, GP128, 16 * (4 * hv + j), 32 * kk, lane), qf[kk], a2[j]);
; #pragma unroll
;                 for (int j = 0; j < 4; ++j) a1[4 * hv + j] = a2[j] * sc;
;                 __builtin_amdgcn_sched_barrier(0); }
	v_sub_f32_e32 v40, v2, v40
	v_sub_f32_e64 v36, v36, |v40|
	v_sub_f32_e32 v40, v2, v41
	v_sub_f32_e64 v37, v37, |v40|
	v_sub_f32_e32 v36, v36, v102
	v_sub_f32_e32 v37, v37, v102
	v_mul_f32_e32 v36, 0x3fb8aa3b, v36
	v_mul_f32_e32 v37, 0x3fb8aa3b, v37
	v_exp_f32_e32 v36, v36
	v_exp_f32_e32 v37, v37
	s_nop 0
	v_pk_mul_f32 v[96:97], v[32:33], v[36:37]
	v_sub_f32_e32 v32, v2, v42
	v_sub_f32_e32 v2, v2, v43
	v_sub_f32_e64 v32, v38, |v32|
	v_sub_f32_e64 v2, v39, |v2|
	v_sub_f32_e32 v32, v32, v102
	v_sub_f32_e32 v2, v2, v102
	v_mul_f32_e32 v32, 0x3fb8aa3b, v32
	v_mul_f32_e32 v2, 0x3fb8aa3b, v2
	v_exp_f32_e32 v32, v32
	v_exp_f32_e32 v33, v2
	v_exp_f32_e32 v2, v46
	v_pk_mul_f32 v[100:101], v[34:35], v[32:33]
	v_cvt_pk_bf16_f32 v32, v44, v45
	v_cvt_pk_bf16_f32 v33, v80, v81
	v_cvt_pk_bf16_f32 v34, v96, v97
	v_cvt_pk_bf16_f32 v35, v100, v101
	v_lshl_add_u64 v[36:37], s[88:89], 0, v[64:65]
	v_add_u32_e32 v69, s4, v170
	global_load_dwordx2 v[98:99], v[36:37], off offset:-128
	global_load_dwordx2 v[94:95], v[36:37], off offset:-96
	global_load_dwordx2 v[92:93], v[36:37], off offset:-64
	global_load_dwordx2 v[90:91], v[36:37], off offset:-32
	global_load_dwordx2 v[88:89], v[36:37], off
	global_load_dwordx2 v[86:87], v[36:37], off offset:32
	global_load_dwordx2 v[84:85], v[36:37], off offset:64
	global_load_dwordx2 v[82:83], v[36:37], off offset:96
	s_waitcnt lgkmcnt(0)
	ds_read_b128 v[214:217], v69
	ds_read_b128 v[218:221], v69 offset:4352
	ds_read_b128 v[222:225], v69 offset:8704
	ds_read_b128 v[226:229], v69 offset:13056
	ds_read_b128 v[230:233], v69 offset:64
	ds_read_b128 v[234:237], v69 offset:4416
	s_waitcnt lgkmcnt(5)
	v_mfma_f32_16x16x32_bf16 v[36:39], v[214:217], v[24:27], 0
	ds_read_b128 v[214:217], v69 offset:8768
	s_waitcnt lgkmcnt(5)
	v_mfma_f32_16x16x32_bf16 v[40:43], v[218:221], v[24:27], 0
	ds_read_b128 v[218:221], v69 offset:13120
	s_waitcnt lgkmcnt(5)
	v_mfma_f32_16x16x32_bf16 v[48:51], v[222:225], v[24:27], 0
	ds_read_b128 v[222:225], v69 offset:128
	s_waitcnt lgkmcnt(5)
	v_mfma_f32_16x16x32_bf16 v[44:47], v[226:229], v[24:27], 0
	ds_read_b128 v[226:229], v69 offset:4480
	s_waitcnt lgkmcnt(5)
	v_mfma_f32_16x16x32_bf16 v[36:39], v[230:233], v[20:23], v[36:39]
	ds_read_b128 v[230:233], v69 offset:8832
	s_waitcnt lgkmcnt(5)
	v_mfma_f32_16x16x32_bf16 v[40:43], v[234:237], v[20:23], v[40:43]
	ds_read_b128 v[234:237], v69 offset:13184
	s_waitcnt lgkmcnt(5)
	v_mfma_f32_16x16x32_bf16 v[48:51], v[214:217], v[20:23], v[48:51]
	ds_read_b128 v[214:217], v69 offset:192
	s_waitcnt lgkmcnt(5)
	v_mfma_f32_16x16x32_bf16 v[44:47], v[218:221], v[20:23], v[44:47]
	ds_read_b128 v[218:221], v69 offset:4544
	s_waitcnt lgkmcnt(5)
	v_mfma_f32_16x16x32_bf16 v[36:39], v[222:225], v[16:19], v[36:39]
	ds_read_b128 v[222:225], v69 offset:8896
	s_waitcnt lgkmcnt(5)
	v_mfma_f32_16x16x32_bf16 v[40:43], v[226:229], v[16:19], v[40:43]
	ds_read_b128 v[226:229], v69 offset:13248
	s_waitcnt lgkmcnt(5)
	v_mfma_f32_16x16x32_bf16 v[48:51], v[230:233], v[16:19], v[48:51]
	s_waitcnt lgkmcnt(4)
	v_mfma_f32_16x16x32_bf16 v[44:47], v[234:237], v[16:19], v[44:47]
	s_waitcnt lgkmcnt(3)
	v_mfma_f32_16x16x32_bf16 v[36:39], v[214:217], v[12:15], v[36:39]
	s_waitcnt lgkmcnt(2)
	v_mfma_f32_16x16x32_bf16 v[40:43], v[218:221], v[12:15], v[40:43]
	s_waitcnt lgkmcnt(1)
	v_mfma_f32_16x16x32_bf16 v[48:51], v[222:225], v[12:15], v[48:51]
	s_waitcnt lgkmcnt(0)
	v_mfma_f32_16x16x32_bf16 v[44:47], v[226:229], v[12:15], v[44:47]
	s_nop 7
	v_pk_mul_f32 v[36:37], v[2:3], v[36:37] op_sel_hi:[0,1]
	v_pk_mul_f32 v[38:39], v[2:3], v[38:39] op_sel_hi:[0,1]
	v_pk_mul_f32 v[40:41], v[2:3], v[40:41] op_sel_hi:[0,1]
	v_pk_mul_f32 v[42:43], v[2:3], v[42:43] op_sel_hi:[0,1]
	v_pk_mul_f32 v[48:49], v[2:3], v[48:49] op_sel_hi:[0,1]
	v_pk_mul_f32 v[50:51], v[2:3], v[50:51] op_sel_hi:[0,1]
	v_pk_mul_f32 v[44:45], v[2:3], v[44:45] op_sel_hi:[0,1]
	v_pk_mul_f32 v[46:47], v[2:3], v[46:47] op_sel_hi:[0,1]
	ds_read_b128 v[214:217], v69 offset:17408
	ds_read_b128 v[218:221], v69 offset:21760
	ds_read_b128 v[222:225], v69 offset:26112
	ds_read_b128 v[226:229], v69 offset:30464
	ds_read_b128 v[230:233], v69 offset:17472
	ds_read_b128 v[234:237], v69 offset:21824
	s_waitcnt lgkmcnt(5)
	v_mfma_f32_16x16x32_bf16 v[104:107], v[214:217], v[24:27], 0
	ds_read_b128 v[214:217], v69 offset:26176
	s_waitcnt lgkmcnt(5)
	v_mfma_f32_16x16x32_bf16 v[108:111], v[218:221], v[24:27], 0
	ds_read_b128 v[218:221], v69 offset:30528
	s_waitcnt lgkmcnt(5)
	v_mfma_f32_16x16x32_bf16 v[112:115], v[222:225], v[24:27], 0
	ds_read_b128 v[222:225], v69 offset:17536
	s_waitcnt lgkmcnt(5)
	v_mfma_f32_16x16x32_bf16 v[116:119], v[226:229], v[24:27], 0
	ds_read_b128 v[226:229], v69 offset:21888
	s_waitcnt lgkmcnt(5)
	v_mfma_f32_16x16x32_bf16 v[104:107], v[230:233], v[20:23], v[104:107]
	ds_read_b128 v[230:233], v69 offset:26240
	s_waitcnt lgkmcnt(5)
	v_mfma_f32_16x16x32_bf16 v[108:111], v[234:237], v[20:23], v[108:111]
	ds_read_b128 v[234:237], v69 offset:30592
	s_waitcnt lgkmcnt(5)
	v_mfma_f32_16x16x32_bf16 v[112:115], v[214:217], v[20:23], v[112:115]
	ds_read_b128 v[214:217], v69 offset:17600
	s_waitcnt lgkmcnt(5)
	v_mfma_f32_16x16x32_bf16 v[116:119], v[218:221], v[20:23], v[116:119]
	ds_read_b128 v[218:221], v69 offset:21952
	s_waitcnt lgkmcnt(5)
	v_mfma_f32_16x16x32_bf16 v[104:107], v[222:225], v[16:19], v[104:107]
	ds_read_b128 v[222:225], v69 offset:26304
	s_waitcnt lgkmcnt(5)
	v_mfma_f32_16x16x32_bf16 v[108:111], v[226:229], v[16:19], v[108:111]
	ds_read_b128 v[226:229], v69 offset:30656
	s_waitcnt lgkmcnt(5)
	v_mfma_f32_16x16x32_bf16 v[112:115], v[230:233], v[16:19], v[112:115]
	s_waitcnt lgkmcnt(4)
; #define MFMA16(a, b, c) __builtin_amdgcn_mfma_f32_16x16x32_bf16((a), (b), (c), 0, 0, 0)
; __device__ __forceinline__ float fexp(float x) { return __builtin_amdgcn_exp2f(x * LOG2E); }
; __device__ __forceinline__ float fsigmoid(float x) { return __builtin_amdgcn_rcpf(1.f + __builtin_amdgcn_exp2f(-LOG2E * x)); }
; __device__ __forceinline__ f32x4 bf4_to_f32(u32x2 w) { return (f32x4){bflo(w.x), bfhi(w.x), bflo(w.y), bfhi(w.y)}; }
; __device__ __forceinline__ void ml_out_unit(LAS unsigned char* lds, const MixBufs& B, int b, int h, int seg, int tid) {
;     ...
;                     for (int j = 0; j < 4; ++j) a2[j] = MFMA16(frag_row(CTc, GP128, 16 * (4 * hv + j), 32 * kk, lane), qf[kk], a2[j]);
; #pragma unroll
;                 for (int j = 0; j < 4; ++j) a1[4 * hv + j] = a2[j] * sc;
;                 __builtin_amdgcn_sched_barrier(0); }
; #pragma unroll
;             for (int ks = 0; ks < 2; ++ks)
; #pragma unroll
;                 for (int vt = 0; vt < 8; ++vt) a1[vt] = MFMA16(frag_tr_perm(lds + O_V, GP128, 32 * ks, 16 * vt, lane), pb[ks], a1[vt]);
;             float den = dsum + sc * qn;
;             den = fmaxf(fabsf(den), fexp(-mt));
;             const float rden = 1.f / den;
;             float s1 = 0.f, s2 = 0.f;
; #pragma unroll
;             for (int vt = 0; vt < 8; ++vt) { const f32x4 op = bf4_to_f32(opv[vt]);
; #pragma unroll
;                 for (int i = 0; i < 4; ++i) { const float x = a1[vt][i] * rden * fsigmoid(op[i]); a1[vt][i] = x; s1 += x; s2 += x * x; } }
	v_mfma_f32_16x16x32_bf16 v[116:119], v[234:237], v[16:19], v[116:119]
	s_waitcnt lgkmcnt(3)
	v_mfma_f32_16x16x32_bf16 v[104:107], v[214:217], v[12:15], v[104:107]
	s_waitcnt lgkmcnt(2)
	v_mfma_f32_16x16x32_bf16 v[108:111], v[218:221], v[12:15], v[108:111]
	s_waitcnt lgkmcnt(1)
	v_mfma_f32_16x16x32_bf16 v[112:115], v[222:225], v[12:15], v[112:115]
	s_waitcnt lgkmcnt(0)
	v_mfma_f32_16x16x32_bf16 v[116:119], v[226:229], v[12:15], v[116:119]
	s_nop 7
	v_pk_mul_f32 v[16:17], v[2:3], v[104:105] op_sel_hi:[0,1]
	v_pk_mul_f32 v[18:19], v[2:3], v[106:107] op_sel_hi:[0,1]
	v_pk_mul_f32 v[20:21], v[2:3], v[108:109] op_sel_hi:[0,1]
	v_pk_mul_f32 v[22:23], v[2:3], v[110:111] op_sel_hi:[0,1]
	v_pk_mul_f32 v[24:25], v[2:3], v[112:113] op_sel_hi:[0,1]
	v_pk_mul_f32 v[26:27], v[2:3], v[114:115] op_sel_hi:[0,1]
	v_pk_mul_f32 v[12:13], v[2:3], v[116:117] op_sel_hi:[0,1]
	v_pk_mul_f32 v[14:15], v[2:3], v[118:119] op_sel_hi:[0,1]
	ds_read_b64_tr_b16 v[104:105], v167 offset:34816
	ds_read_b64_tr_b16 v[106:107], v167 offset:39168
	ds_read_b64_tr_b16 v[110:111], v167 offset:39200
	ds_read_b64_tr_b16 v[108:109], v167 offset:34848
	ds_read_b64_tr_b16 v[112:113], v167 offset:34880
	ds_read_b64_tr_b16 v[116:117], v167 offset:34912
	ds_read_b64_tr_b16 v[114:115], v167 offset:39232
	ds_read_b64_tr_b16 v[118:119], v167 offset:39264
	s_waitcnt lgkmcnt(6)
	v_mfma_f32_16x16x32_bf16 v[36:39], v[104:107], v[28:31], v[36:39]
	v_mov_b32_e32 v73, v81
	v_mov_b32_e32 v77, v96
	v_mov_b32_e32 v75, v97
	s_waitcnt lgkmcnt(4)
	v_mfma_f32_16x16x32_bf16 v[104:107], v[108:111], v[28:31], v[40:43]
	s_nop 2
	ds_read_b64_tr_b16 v[40:41], v167 offset:34944
	ds_read_b64_tr_b16 v[42:43], v167 offset:39296
	ds_read_b64_tr_b16 v[110:111], v167 offset:39328
	v_mov_b32_e32 v71, v100
	v_mov_b32_e32 v69, v101
	s_waitcnt lgkmcnt(4)
	v_mfma_f32_16x16x32_bf16 v[48:51], v[112:115], v[28:31], v[48:51]
	s_xor_b32 s7, s7, 1
	s_add_u32 s14, s14, 0x10000
	s_addc_u32 s15, s15, 0
	s_waitcnt lgkmcnt(3)
	v_mfma_f32_16x16x32_bf16 v[44:47], v[116:119], v[28:31], v[44:47]
	ds_read_b64_tr_b16 v[108:109], v167 offset:34976
	ds_read_b64_tr_b16 v[112:113], v167 offset:35008
	ds_read_b64_tr_b16 v[116:117], v167 offset:35040
	ds_read_b64_tr_b16 v[114:115], v167 offset:39360
	ds_read_b64_tr_b16 v[118:119], v167 offset:39392
	s_add_u32 s12, s12, 64
	s_addc_u32 s13, s13, 0
	s_waitcnt lgkmcnt(6)
	v_mfma_f32_16x16x32_bf16 v[16:19], v[40:43], v[28:31], v[16:19]
	ds_read_b64_tr_b16 v[40:41], v167 offset:43520
	s_add_i32 s20, s20, 1
	s_add_i32 s26, s26, 8
	s_waitcnt lgkmcnt(5)
	v_mfma_f32_16x16x32_bf16 v[20:23], v[108:111], v[28:31], v[20:23]
	s_cmp_eq_u32 s14, 0x80000
	s_waitcnt lgkmcnt(2)
	v_mfma_f32_16x16x32_bf16 v[108:111], v[112:115], v[28:31], v[24:27]
	ds_read_b64_tr_b16 v[42:43], v167 offset:47872
	s_nop 1
	ds_read_b64_tr_b16 v[26:27], v167 offset:47904
	s_waitcnt lgkmcnt(3)
	v_mfma_f32_16x16x32_bf16 v[112:115], v[116:119], v[28:31], v[12:15]
	ds_read_b64_tr_b16 v[24:25], v167 offset:43552
	s_nop 1
	ds_read_b64_tr_b16 v[12:13], v167 offset:43584
	ds_read_b64_tr_b16 v[116:117], v167 offset:43616
	ds_read_b64_tr_b16 v[14:15], v167 offset:47936
	ds_read_b64_tr_b16 v[118:119], v167 offset:47968
	ds_read_b64_tr_b16 v[120:121], v167 offset:43648
	ds_read_b64_tr_b16 v[124:125], v167 offset:43680
	ds_read_b64_tr_b16 v[128:129], v167 offset:43712
	ds_read_b64_tr_b16 v[132:133], v167 offset:43744
	ds_read_b64_tr_b16 v[122:123], v167 offset:48000
	ds_read_b64_tr_b16 v[126:127], v167 offset:48032
	ds_read_b64_tr_b16 v[130:131], v167 offset:48064
	ds_read_b64_tr_b16 v[134:135], v167 offset:48096
	s_waitcnt lgkmcnt(14)
	v_mfma_f32_16x16x32_bf16 v[40:43], v[40:43], v[32:35], v[36:39]
	s_waitcnt lgkmcnt(9)
	v_mfma_f32_16x16x32_bf16 v[36:39], v[12:15], v[32:35], v[48:51]
	v_add_f32_e64 v12, v72, v78
	v_add_f32_e64 v13, v73, v79
	v_pk_add_f32 v[12:13], v[12:13], v[76:77]
	v_mfma_f32_16x16x32_bf16 v[28:31], v[24:27], v[32:35], v[104:107]
	s_waitcnt lgkmcnt(8)
	v_mfma_f32_16x16x32_bf16 v[24:27], v[116:119], v[32:35], v[44:47]
	s_nop 2
	v_add_f32_e64 v44, v74, v12
	v_add_f32_e64 v45, v75, v13
	s_waitcnt lgkmcnt(3)
	v_mfma_f32_16x16x32_bf16 v[12:15], v[120:123], v[32:35], v[16:19]
	s_nop 2
	v_add_f32_e64 v16, v70, v44
	v_add_f32_e64 v17, v71, v45
	v_mul_f32_e32 v44, 0xbfb8aa3b, v102
	v_pk_add_f32 v[16:17], v[68:69], v[16:17]
	ds_bpermute_b32 v18, v200, v16
	ds_bpermute_b32 v19, v200, v17
	v_exp_f32_e32 v48, v44
	s_waitcnt lgkmcnt(4)
	v_mfma_f32_16x16x32_bf16 v[20:23], v[124:127], v[32:35], v[20:23]
	s_waitcnt lgkmcnt(0)
	v_pk_add_f32 v[16:17], v[16:17], v[18:19]
	ds_bpermute_b32 v18, v199, v16
	ds_bpermute_b32 v19, v199, v17
	v_mfma_f32_16x16x32_bf16 v[44:47], v[128:131], v[32:35], v[108:111]
	s_waitcnt lgkmcnt(0)
	v_pk_add_f32 v[16:17], v[16:17], v[18:19]
	s_nop 0
	v_fmac_f32_e32 v17, v2, v16
	v_max_f32_e64 v2, |v17|, v48
	v_div_scale_f32 v48, s[4:5], v2, v2, 1.0
	v_rcp_f32_e32 v49, v48
	v_mfma_f32_16x16x32_bf16 v[16:19], v[132:135], v[32:35], v[112:115]
	s_waitcnt vmcnt(7)
	v_and_b32_e32 v35, 0xffff0000, v99
	s_brev_b32 s4, 60
	v_fma_f32 v32, -v48, v49, 1.0
	v_fmac_f32_e32 v49, v32, v49
	v_div_scale_f32 v32, vcc, 1.0, v2, 1.0
	v_mul_f32_e32 v33, v32, v49
	v_fma_f32 v34, -v48, v33, v32
	v_fmac_f32_e32 v33, v34, v49
	v_fma_f32 v32, -v48, v33, v32
	v_div_fmas_f32 v32, v32, v49, v33
	v_div_fixup_f32 v2, v32, v2, 1.0
	v_lshlrev_b32_e32 v32, 16, v98
	v_and_b32_e32 v33, 0xffff0000, v98
	v_mul_f32_e32 v32, 0xbfb8aa3b, v32
	v_exp_f32_e32 v32, v32
	v_mul_f32_e32 v33, 0xbfb8aa3b, v33
	v_exp_f32_e32 v33, v33
	v_lshlrev_b32_e32 v34, 16, v99
	v_add_f32_e32 v32, 1.0, v32
	v_rcp_f32_e32 v48, v32
	v_add_f32_e32 v32, 1.0, v33
	v_mul_f32_e32 v33, 0xbfb8aa3b, v34
	v_exp_f32_e32 v33, v33
	v_mul_f32_e32 v34, 0xbfb8aa3b, v35
	v_exp_f32_e32 v34, v34
	v_rcp_f32_e32 v49, v32
	v_add_f32_e32 v32, 1.0, v33
	v_rcp_f32_e32 v50, v32
	v_add_f32_e32 v32, 1.0, v34
	v_rcp_f32_e32 v51, v32
	s_waitcnt vmcnt(6)
; #define LAS __attribute__((address_space(3)))
; __device__ __forceinline__ float fsigmoid(float x) { return __builtin_amdgcn_rcpf(1.f + __builtin_amdgcn_exp2f(-LOG2E * x)); }
; __device__ __forceinline__ f32x4 bf4_to_f32(u32x2 w) { return (f32x4){bflo(w.x), bfhi(w.x), bflo(w.y), bfhi(w.y)}; }
; __device__ __forceinline__ void ml_out_unit(LAS unsigned char* lds, const MixBufs& B, int b, int h, int seg, int tid) {
;     ...
;             for (int vt = 0; vt < 8; ++vt) { const f32x4 op = bf4_to_f32(opv[vt]);
; #pragma unroll
;                 for (int i = 0; i < 4; ++i) { const float x = a1[vt][i] * rden * fsigmoid(op[i]); a1[vt][i] = x; s1 += x; s2 += x * x; } }
;             s1 += __shfl_xor(s1, 16); s1 += __shfl_xor(s1, 32); s2 += __shfl_xor(s2, 16); s2 += __shfl_xor(s2, 32);
;             const float mu = s1 * (1.f / 128.f), var = s2 * (1.f / 128.f) - mu * mu, rstd = 1.f / sqrtf(fmaxf(var, 0.f) + EPS);
; #pragma unroll
;             for (int vt = 0; vt < 8; ++vt) { const int cl = 16 * vt + 4 * g; const f32x4 xc = bf4_to_f32(*(const LAS u32x2*)(lds + O_XC + (16 * ti + c) * GP128 + cl * 2)), gn = *(const LAS f32x4*)(GN + cl), sk = *(const LAS f32x4*)(SK + cl);
	v_lshlrev_b32_e32 v32, 16, v94
	v_and_b32_e32 v33, 0xffff0000, v94
	v_mul_f32_e32 v32, 0xbfb8aa3b, v32
	v_exp_f32_e32 v32, v32
	v_mul_f32_e32 v33, 0xbfb8aa3b, v33
	v_exp_f32_e32 v33, v33
	v_lshlrev_b32_e32 v34, 16, v95
	v_add_f32_e32 v32, 1.0, v32
	v_and_b32_e32 v35, 0xffff0000, v95
	v_rcp_f32_e32 v68, v32
	v_add_f32_e32 v32, 1.0, v33
	v_mul_f32_e32 v33, 0xbfb8aa3b, v34
	v_exp_f32_e32 v33, v33
	v_mul_f32_e32 v34, 0xbfb8aa3b, v35
	v_exp_f32_e32 v34, v34
	v_rcp_f32_e32 v69, v32
	v_add_f32_e32 v32, 1.0, v33
	v_rcp_f32_e32 v70, v32
	v_add_f32_e32 v32, 1.0, v34
	v_rcp_f32_e32 v71, v32
	s_waitcnt vmcnt(5)
	v_lshlrev_b32_e32 v32, 16, v92
	v_and_b32_e32 v33, 0xffff0000, v92
	v_mul_f32_e32 v32, 0xbfb8aa3b, v32
	v_exp_f32_e32 v32, v32
	v_mul_f32_e32 v33, 0xbfb8aa3b, v33
	v_exp_f32_e32 v33, v33
	v_lshlrev_b32_e32 v34, 16, v93
	v_add_f32_e32 v32, 1.0, v32
	v_and_b32_e32 v35, 0xffff0000, v93
	v_rcp_f32_e32 v72, v32
	v_add_f32_e32 v32, 1.0, v33
	v_mul_f32_e32 v33, 0xbfb8aa3b, v34
	v_exp_f32_e32 v33, v33
	v_mul_f32_e32 v34, 0xbfb8aa3b, v35
	v_exp_f32_e32 v34, v34
	v_rcp_f32_e32 v73, v32
	v_add_f32_e32 v32, 1.0, v33
	v_rcp_f32_e32 v74, v32
	v_add_f32_e32 v32, 1.0, v34
	v_rcp_f32_e32 v75, v32
	s_waitcnt vmcnt(4)
	v_lshlrev_b32_e32 v32, 16, v90
	v_and_b32_e32 v33, 0xffff0000, v90
	v_mul_f32_e32 v32, 0xbfb8aa3b, v32
	v_exp_f32_e32 v32, v32
	v_mul_f32_e32 v33, 0xbfb8aa3b, v33
	v_exp_f32_e32 v33, v33
	v_lshlrev_b32_e32 v34, 16, v91
	v_add_f32_e32 v32, 1.0, v32
	v_and_b32_e32 v35, 0xffff0000, v91
	v_rcp_f32_e32 v76, v32
	v_add_f32_e32 v32, 1.0, v33
	v_mul_f32_e32 v33, 0xbfb8aa3b, v34
	v_exp_f32_e32 v33, v33
	v_mul_f32_e32 v34, 0xbfb8aa3b, v35
	v_exp_f32_e32 v34, v34
	v_rcp_f32_e32 v77, v32
	v_add_f32_e32 v32, 1.0, v33
	v_rcp_f32_e32 v78, v32
	v_add_f32_e32 v32, 1.0, v34
	v_rcp_f32_e32 v79, v32
	s_waitcnt vmcnt(3)
	v_lshlrev_b32_e32 v32, 16, v88
	v_and_b32_e32 v33, 0xffff0000, v88
	v_mul_f32_e32 v32, 0xbfb8aa3b, v32
	v_exp_f32_e32 v32, v32
	v_mul_f32_e32 v33, 0xbfb8aa3b, v33
	v_exp_f32_e32 v33, v33
	v_pk_mul_f32 v[94:95], v[2:3], v[20:21] op_sel_hi:[0,1]
	s_waitcnt vmcnt(1)
	v_lshlrev_b32_e32 v20, 16, v84
	v_lshlrev_b32_e32 v34, 16, v89
	v_add_f32_e32 v32, 1.0, v32
	v_and_b32_e32 v21, 0xffff0000, v84
	v_mul_f32_e32 v20, 0xbfb8aa3b, v20
	v_and_b32_e32 v35, 0xffff0000, v89
	v_rcp_f32_e32 v80, v32
	v_add_f32_e32 v32, 1.0, v33
	v_mul_f32_e32 v33, 0xbfb8aa3b, v34
	v_exp_f32_e32 v20, v20
	v_mul_f32_e32 v21, 0xbfb8aa3b, v21
	v_exp_f32_e32 v33, v33
	v_mul_f32_e32 v34, 0xbfb8aa3b, v35
	v_exp_f32_e32 v21, v21
	v_exp_f32_e32 v34, v34
	v_add_f32_e32 v20, 1.0, v20
	v_rcp_f32_e32 v81, v32
	v_add_f32_e32 v32, 1.0, v33
	v_pk_mul_f32 v[92:93], v[2:3], v[22:23] op_sel_hi:[0,1]
	v_lshlrev_b32_e32 v22, 16, v85
	v_rcp_f32_e32 v84, v20
	v_add_f32_e32 v20, 1.0, v21
	v_rcp_f32_e32 v88, v32
	v_add_f32_e32 v32, 1.0, v34
	v_and_b32_e32 v23, 0xffff0000, v85
	v_rcp_f32_e32 v85, v20
	v_mul_f32_e32 v20, 0xbfb8aa3b, v22
	v_rcp_f32_e32 v89, v32
	v_lshlrev_b32_e32 v32, 16, v86
	v_exp_f32_e32 v20, v20
	v_mul_f32_e32 v21, 0xbfb8aa3b, v23
	v_and_b32_e32 v33, 0xffff0000, v86
	v_mul_f32_e32 v32, 0xbfb8aa3b, v32
	v_exp_f32_e32 v21, v21
	v_exp_f32_e32 v32, v32
	v_mul_f32_e32 v33, 0xbfb8aa3b, v33
	v_exp_f32_e32 v33, v33
	v_add_f32_e32 v20, 1.0, v20
	v_rcp_f32_e32 v98, v20
	v_add_f32_e32 v20, 1.0, v21
	v_lshlrev_b32_e32 v34, 16, v87
	v_add_f32_e32 v32, 1.0, v32
	v_rcp_f32_e32 v99, v20
	s_waitcnt vmcnt(0)
	v_lshlrev_b32_e32 v20, 16, v82
	v_lshlrev_b32_e32 v22, 16, v83
	v_and_b32_e32 v35, 0xffff0000, v87
	v_rcp_f32_e32 v86, v32
	v_add_f32_e32 v32, 1.0, v33
	v_mul_f32_e32 v33, 0xbfb8aa3b, v34
	v_and_b32_e32 v21, 0xffff0000, v82
	v_mul_f32_e32 v20, 0xbfb8aa3b, v20
	v_and_b32_e32 v23, 0xffff0000, v83
	v_pk_mul_f32 v[102:103], v[2:3], v[16:17] op_sel_hi:[0,1]
	v_mul_f32_e32 v16, 0xbfb8aa3b, v22
	v_exp_f32_e32 v33, v33
	v_mul_f32_e32 v34, 0xbfb8aa3b, v35
	v_exp_f32_e32 v20, v20
	v_mul_f32_e32 v21, 0xbfb8aa3b, v21
	v_exp_f32_e32 v16, v16
	v_mul_f32_e32 v17, 0xbfb8aa3b, v23
	v_exp_f32_e32 v34, v34
	v_exp_f32_e32 v21, v21
	v_exp_f32_e32 v17, v17
	v_rcp_f32_e32 v87, v32
	v_add_f32_e32 v32, 1.0, v33
	v_add_f32_e32 v20, 1.0, v20
	v_add_f32_e32 v16, 1.0, v16
	v_rcp_f32_e32 v90, v32
	v_add_f32_e32 v32, 1.0, v34
	v_rcp_f32_e32 v82, v20
	v_add_f32_e32 v20, 1.0, v21
	v_rcp_f32_e32 v104, v16
	v_add_f32_e32 v16, 1.0, v17
	v_rcp_f32_e32 v91, v32
	v_rcp_f32_e32 v83, v20
	v_rcp_f32_e32 v105, v16
	v_pk_mul_f32 v[106:107], v[2:3], v[18:19] op_sel_hi:[0,1]
	ds_read_b64 v[32:33], v168 offset:52224
	ds_read_b128 v[16:19], v171
	ds_read_b128 v[20:23], v172
	v_pk_mul_f32 v[114:115], v[2:3], v[40:41] op_sel_hi:[0,1]
	v_pk_mul_f32 v[40:41], v[48:49], v[114:115]
	v_pk_mul_f32 v[108:109], v[2:3], v[42:43] op_sel_hi:[0,1]
	s_waitcnt lgkmcnt(2)
	v_lshlrev_b32_e32 v112, 16, v33
	v_and_b32_e32 v113, 0xffff0000, v33
	v_add_f32_e32 v33, 0, v40
	v_pk_mul_f32 v[96:97], v[2:3], v[44:45] op_sel_hi:[0,1]
	v_pk_mul_f32 v[34:35], v[50:51], v[108:109]
	ds_read_b64 v[44:45], v169 offset:52224
	ds_read_b64 v[202:203], v192 offset:52224
	ds_read_b64 v[204:205], v193 offset:52224
	v_add_f32_e32 v33, v41, v33
	v_mul_f32_e32 v42, v41, v41
	v_pk_fma_f32 v[40:41], v[40:41], v[40:41], v[42:43] op_sel_hi:[1,1,0]
	v_add_f32_e32 v42, v34, v33
	v_pk_mul_f32 v[122:123], v[2:3], v[28:29] op_sel_hi:[0,1]
	v_lshlrev_b32_e32 v120, 16, v32
	v_and_b32_e32 v121, 0xffff0000, v32
	v_pk_fma_f32 v[32:33], v[34:35], v[34:35], v[40:41]
	v_add_f32_e32 v124, v35, v42
	v_mul_f32_e32 v34, v35, v35
	v_pk_mul_f32 v[28:29], v[68:69], v[122:123]
	v_pk_mul_f32 v[100:101], v[2:3], v[46:47] op_sel_hi:[0,1]
	v_pk_add_f32 v[46:47], v[34:35], v[32:33] op_sel_hi:[0,1]
	v_pk_mul_f32 v[118:119], v[2:3], v[30:31] op_sel_hi:[0,1]
	s_waitcnt lgkmcnt(2)
; #define LAS __attribute__((address_space(3)))
; __device__ __forceinline__ float fsigmoid(float x) { return __builtin_amdgcn_rcpf(1.f + __builtin_amdgcn_exp2f(-LOG2E * x)); }
; __device__ __forceinline__ f32x4 bf4_to_f32(u32x2 w) { return (f32x4){bflo(w.x), bfhi(w.x), bflo(w.y), bfhi(w.y)}; }
; __device__ __forceinline__ void ml_out_unit(LAS unsigned char* lds, const MixBufs& B, int b, int h, int seg, int tid) {
;     ...
;                 for (int i = 0; i < 4; ++i) { const float x = a1[vt][i] * rden * fsigmoid(op[i]); a1[vt][i] = x; s1 += x; s2 += x * x; } }
;             s1 += __shfl_xor(s1, 16); s1 += __shfl_xor(s1, 32); s2 += __shfl_xor(s2, 16); s2 += __shfl_xor(s2, 32);
;             const float mu = s1 * (1.f / 128.f), var = s2 * (1.f / 128.f) - mu * mu, rstd = 1.f / sqrtf(fmaxf(var, 0.f) + EPS);
; #pragma unroll
;             for (int vt = 0; vt < 8; ++vt) { const int cl = 16 * vt + 4 * g; const f32x4 xc = bf4_to_f32(*(const LAS u32x2*)(lds + O_XC + (16 * ti + c) * GP128 + cl * 2)), gn = *(const LAS f32x4*)(GN + cl), sk = *(const LAS f32x4*)(SK + cl);
	v_lshlrev_b32_e32 v116, 16, v45
	v_and_b32_e32 v117, 0xffff0000, v45
	v_add_f32_e32 v45, v28, v124
	v_pk_mul_f32 v[30:31], v[70:71], v[118:119]
	v_pk_fma_f32 v[46:47], v[28:29], v[28:29], v[46:47]
	v_add_f32_e32 v45, v29, v45
	v_mul_f32_e32 v28, v29, v29
	v_pk_add_f32 v[28:29], v[28:29], v[46:47] op_sel_hi:[0,1]
	v_lshlrev_b32_e32 v126, 16, v44
	v_and_b32_e32 v127, 0xffff0000, v44
	v_add_f32_e32 v44, v30, v45
	v_pk_mul_f32 v[36:37], v[2:3], v[36:37] op_sel_hi:[0,1]
	v_pk_fma_f32 v[28:29], v[30:31], v[30:31], v[28:29]
	v_add_f32_e32 v186, v31, v44
	v_mul_f32_e32 v30, v31, v31
	v_pk_mul_f32 v[210:211], v[72:73], v[36:37]
	v_pk_add_f32 v[128:129], v[30:31], v[28:29] op_sel_hi:[0,1]
	v_pk_mul_f32 v[124:125], v[2:3], v[38:39] op_sel_hi:[0,1]
	v_add_f32_e32 v186, v210, v186
	v_pk_mul_f32 v[208:209], v[74:75], v[124:125]
	v_pk_fma_f32 v[128:129], v[210:211], v[210:211], v[128:129]
	v_add_f32_e32 v201, v211, v186
	v_mul_f32_e32 v186, v211, v211
	v_pk_add_f32 v[210:211], v[186:187], v[128:129] op_sel_hi:[0,1]
	v_add_f32_e32 v186, v208, v201
	v_pk_mul_f32 v[24:25], v[2:3], v[24:25] op_sel_hi:[0,1]
	s_waitcnt lgkmcnt(1)
	v_lshlrev_b32_e32 v38, 16, v203
	v_and_b32_e32 v39, 0xffff0000, v203
	v_lshlrev_b32_e32 v128, 16, v202
	v_and_b32_e32 v129, 0xffff0000, v202
	v_pk_fma_f32 v[202:203], v[208:209], v[208:209], v[210:211]
	v_add_f32_e32 v201, v209, v186
	v_mul_f32_e32 v186, v209, v209
	v_pk_mul_f32 v[210:211], v[76:77], v[24:25]
	v_pk_add_f32 v[202:203], v[186:187], v[202:203] op_sel_hi:[0,1]
	v_pk_mul_f32 v[26:27], v[2:3], v[26:27] op_sel_hi:[0,1]
	v_add_f32_e32 v186, v210, v201
	v_pk_mul_f32 v[208:209], v[78:79], v[26:27]
	v_pk_fma_f32 v[202:203], v[210:211], v[210:211], v[202:203]
	v_add_f32_e32 v201, v211, v186
	v_mul_f32_e32 v186, v211, v211
	v_pk_add_f32 v[202:203], v[186:187], v[202:203] op_sel_hi:[0,1]
	v_add_f32_e32 v186, v208, v201
	v_pk_mul_f32 v[12:13], v[2:3], v[12:13] op_sel_hi:[0,1]
	v_pk_fma_f32 v[202:203], v[208:209], v[208:209], v[202:203]
	v_add_f32_e32 v201, v209, v186
	v_mul_f32_e32 v186, v209, v209
	v_pk_mul_f32 v[212:213], v[80:81], v[12:13]
	v_pk_add_f32 v[202:203], v[186:187], v[202:203] op_sel_hi:[0,1]
	v_pk_mul_f32 v[14:15], v[2:3], v[14:15] op_sel_hi:[0,1]
	v_add_f32_e32 v2, v212, v201
	v_pk_mul_f32 v[208:209], v[88:89], v[14:15]
	v_pk_fma_f32 v[202:203], v[212:213], v[212:213], v[202:203]
	v_add_f32_e32 v186, v213, v2
	v_mul_f32_e32 v2, v213, v213
	v_pk_add_f32 v[202:203], v[2:3], v[202:203] op_sel_hi:[0,1]
	v_add_f32_e32 v2, v208, v186
	v_pk_mul_f32 v[130:131], v[86:87], v[94:95]
	v_pk_fma_f32 v[202:203], v[208:209], v[208:209], v[202:203]
	v_add_f32_e32 v186, v209, v2
	v_mul_f32_e32 v2, v209, v209
	v_mov_b32_e32 v210, v130
	v_mov_b32_e32 v211, v209
	v_pk_add_f32 v[202:203], v[2:3], v[202:203] op_sel_hi:[0,1]
	v_add_f32_e32 v2, v130, v186
	v_pk_mul_f32 v[132:133], v[90:91], v[92:93]
	v_pk_fma_f32 v[202:203], v[210:211], v[210:211], v[202:203]
	v_add_f32_e32 v186, v131, v2
	v_mul_f32_e32 v2, v131, v131
	v_mov_b32_e32 v134, v132
	v_mov_b32_e32 v135, v131
	v_pk_add_f32 v[130:131], v[2:3], v[202:203] op_sel_hi:[0,1]
	v_add_f32_e32 v2, v132, v186
	v_pk_mul_f32 v[136:137], v[84:85], v[96:97]
	v_pk_fma_f32 v[130:131], v[134:135], v[134:135], v[130:131]
	v_add_f32_e32 v132, v133, v2
	v_mul_f32_e32 v2, v133, v133
	v_mov_b32_e32 v140, v136
	v_mov_b32_e32 v141, v133
	v_pk_add_f32 v[130:131], v[2:3], v[130:131] op_sel_hi:[0,1]
	v_add_f32_e32 v2, v136, v132
	v_pk_mul_f32 v[138:139], v[98:99], v[100:101]
	v_pk_fma_f32 v[130:131], v[140:141], v[140:141], v[130:131]
	v_add_f32_e32 v132, v137, v2
	v_mul_f32_e32 v2, v137, v137
	v_mov_b32_e32 v142, v138
	v_mov_b32_e32 v143, v137
	v_pk_add_f32 v[130:131], v[2:3], v[130:131] op_sel_hi:[0,1]
	v_add_f32_e32 v2, v138, v132
	v_pk_mul_f32 v[144:145], v[82:83], v[102:103]
	v_pk_fma_f32 v[130:131], v[142:143], v[142:143], v[130:131]
	v_add_f32_e32 v132, v139, v2
	v_mul_f32_e32 v2, v139, v139
	v_mov_b32_e32 v148, v144
	v_mov_b32_e32 v149, v139
	v_pk_add_f32 v[130:131], v[2:3], v[130:131] op_sel_hi:[0,1]
	v_add_f32_e32 v2, v144, v132
	v_pk_mul_f32 v[146:147], v[104:105], v[106:107]
	v_pk_fma_f32 v[130:131], v[148:149], v[148:149], v[130:131]
	v_add_f32_e32 v132, v145, v2
	v_mul_f32_e32 v2, v145, v145
	v_mov_b32_e32 v150, v146
	v_mov_b32_e32 v151, v145
	v_pk_add_f32 v[130:131], v[2:3], v[130:131] op_sel_hi:[0,1]
	v_pk_fma_f32 v[130:131], v[150:151], v[150:151], v[130:131]
	v_mul_f32_e32 v206, v147, v147
	v_add_f32_e32 v207, v146, v132
	v_mov_b32_e32 v131, v147
	v_pk_add_f32 v[130:131], v[130:131], v[206:207]
	ds_bpermute_b32 v141, v200, v131
	ds_bpermute_b32 v140, v200, v130
	ds_read_b128 v[32:35], v173
	ds_read_b128 v[40:43], v174
	ds_read_b128 v[28:31], v175
	ds_read_b128 v[44:47], v176
	ds_read_b128 v[132:135], v177
	ds_read_b128 v[136:139], v178
	v_lshl_add_u64 v[110:111], s[88:89], 0, v[66:67]
	s_waitcnt lgkmcnt(6)
	v_pk_add_f32 v[130:131], v[130:131], v[140:141]
	ds_bpermute_b32 v201, v199, v131
	ds_bpermute_b32 v200, v199, v130
	ds_read_b64 v[202:203], v194 offset:52224
	ds_read_b128 v[140:143], v179
	ds_read_b128 v[144:147], v180
	v_lshlrev_b32_e32 v148, 16, v205
	v_and_b32_e32 v149, 0xffff0000, v205
	s_waitcnt lgkmcnt(2)
; #define GAS __attribute__((address_space(1)))
; #define LAS __attribute__((address_space(3)))
; __device__ __forceinline__ f32x4 bf4_to_f32(u32x2 w) { return (f32x4){bflo(w.x), bfhi(w.x), bflo(w.y), bfhi(w.y)}; }
; __device__ __forceinline__ u32x2 f32_to_bf4(f32x4 v) { u32x2 w; w.x = cvtpk(v[0], v[1]); w.y = cvtpk(v[2], v[3]); return w; }
; __device__ __forceinline__ void ml_out_unit(LAS unsigned char* lds, const MixBufs& B, int b, int h, int seg, int tid) {
;     ...
;             s1 += __shfl_xor(s1, 16); s1 += __shfl_xor(s1, 32); s2 += __shfl_xor(s2, 16); s2 += __shfl_xor(s2, 32);
;             const float mu = s1 * (1.f / 128.f), var = s2 * (1.f / 128.f) - mu * mu, rstd = 1.f / sqrtf(fmaxf(var, 0.f) + EPS);
; #pragma unroll
;             for (int vt = 0; vt < 8; ++vt) { const int cl = 16 * vt + 4 * g; const f32x4 xc = bf4_to_f32(*(const LAS u32x2*)(lds + O_XC + (16 * ti + c) * GP128 + cl * 2)), gn = *(const LAS f32x4*)(GN + cl), sk = *(const LAS f32x4*)(SK + cl);
;                 f32x4 r;
; #pragma unroll
;                 for (int i = 0; i < 4; ++i) r[i] = (a1[vt][i] - mu) * rstd * gn[i] + sk[i] * xc[i];
;                 *(GAS u32x2*)(B.A_b + trow * 1024 + h * 128 + cl) = f32_to_bf4(r); }
	v_lshlrev_b32_e32 v210, 16, v202
	v_pk_add_f32 v[130:131], v[130:131], v[200:201]
	v_and_b32_e32 v211, 0xffff0000, v202
	v_pk_mul_f32 v[130:131], v[130:131], s[4:5] op_sel_hi:[1,0]
	v_lshlrev_b32_e32 v208, 16, v203
	v_fma_f32 v2, -v131, v131, v130
	v_max_f32_e32 v2, 0, v2
	v_add_f32_e32 v2, 0x358637bd, v2
	v_mul_f32_e32 v186, 0x4f800000, v2
	v_cmp_gt_f32_e32 vcc, s68, v2
	v_pk_fma_f32 v[48:49], v[48:49], v[114:115], v[130:131] op_sel:[0,0,1] neg_lo:[0,0,1] neg_hi:[0,0,1]
	v_lshlrev_b32_e32 v150, 16, v204
	v_cndmask_b32_e32 v2, v2, v186, vcc
	v_sqrt_f32_e32 v186, v2
	v_and_b32_e32 v151, 0xffff0000, v204
	ds_read_b64 v[200:201], v195 offset:52224
	ds_read_b64 v[204:205], v196 offset:52224
	ds_read_b64 v[206:207], v197 offset:52224
	v_pk_fma_f32 v[12:13], v[80:81], v[12:13], v[130:131] op_sel:[0,0,1] neg_lo:[0,0,1] neg_hi:[0,0,1]
	v_add_u32_e32 v199, -1, v186
	v_fma_f32 v209, -v199, v186, v2
	v_cmp_ge_f32_e64 s[4:5], 0, v209
	v_add_u32_e32 v209, 1, v186
	v_pk_fma_f32 v[14:15], v[88:89], v[14:15], v[130:131] op_sel:[0,0,1] neg_lo:[0,0,1] neg_hi:[0,0,1]
	v_cndmask_b32_e64 v199, v186, v199, s[4:5]
	v_fma_f32 v186, -v209, v186, v2
	v_cmp_lt_f32_e64 s[4:5], 0, v186
	s_nop 1
	v_cndmask_b32_e64 v186, v199, v209, s[4:5]
	v_mul_f32_e32 v199, 0x37800000, v186
	v_cndmask_b32_e32 v186, v186, v199, vcc
	v_cmp_class_f32_e32 vcc, v2, v1
	v_and_b32_e32 v209, 0xffff0000, v203
	s_nop 0
	v_cndmask_b32_e32 v2, v186, v2, vcc
	v_div_scale_f32 v186, s[4:5], v2, v2, 1.0
	v_rcp_f32_e32 v199, v186
	s_mov_b64 s[4:5], 0x400
	v_lshl_add_u64 v[60:61], v[60:61], 0, s[4:5]
	s_mov_b64 s[4:5], 0x98000
	v_fma_f32 v202, -v186, v199, 1.0
	v_fmac_f32_e32 v199, v202, v199
	v_div_scale_f32 v202, vcc, 1.0, v2, 1.0
	v_mul_f32_e32 v203, v202, v199
	v_fma_f32 v212, -v186, v203, v202
	v_fmac_f32_e32 v203, v212, v199
	v_fma_f32 v186, -v186, v203, v202
	v_div_fmas_f32 v186, v186, v199, v203
	v_div_fixup_f32 v2, v186, v2, 1.0
	v_pk_mul_f32 v[48:49], v[48:49], v[2:3] op_sel_hi:[1,0]
	v_pk_mul_f32 v[12:13], v[12:13], v[2:3] op_sel_hi:[1,0]
	v_pk_mul_f32 v[16:17], v[16:17], v[48:49]
	v_pk_mul_f32 v[14:15], v[14:15], v[2:3] op_sel_hi:[1,0]
	v_pk_fma_f32 v[16:17], v[20:21], v[120:121], v[16:17]
	v_pk_fma_f32 v[20:21], v[50:51], v[108:109], v[130:131] op_sel:[0,0,1] neg_lo:[0,0,1] neg_hi:[0,0,1]
	v_cvt_pk_bf16_f32 v16, v16, v17
	v_pk_mul_f32 v[20:21], v[20:21], v[2:3] op_sel_hi:[1,0]
	s_waitcnt lgkmcnt(4)
	v_pk_mul_f32 v[12:13], v[140:141], v[12:13]
	v_pk_mul_f32 v[18:19], v[18:19], v[20:21]
	v_pk_mul_f32 v[14:15], v[142:143], v[14:15]
	v_pk_fma_f32 v[18:19], v[22:23], v[112:113], v[18:19]
	s_waitcnt lgkmcnt(3)
	v_pk_fma_f32 v[12:13], v[144:145], v[210:211], v[12:13]
	v_cvt_pk_bf16_f32 v17, v18, v19
	global_store_dwordx2 v[110:111], v[16:17], off offset:-128
	v_pk_fma_f32 v[16:17], v[68:69], v[122:123], v[130:131] op_sel:[0,0,1] neg_lo:[0,0,1] neg_hi:[0,0,1]
	v_pk_fma_f32 v[18:19], v[70:71], v[118:119], v[130:131] op_sel:[0,0,1] neg_lo:[0,0,1] neg_hi:[0,0,1]
	v_pk_mul_f32 v[16:17], v[16:17], v[2:3] op_sel_hi:[1,0]
	v_pk_mul_f32 v[18:19], v[18:19], v[2:3] op_sel_hi:[1,0]
	v_pk_mul_f32 v[16:17], v[32:33], v[16:17]
	v_pk_mul_f32 v[18:19], v[34:35], v[18:19]
	v_pk_fma_f32 v[16:17], v[40:41], v[126:127], v[16:17]
	v_pk_fma_f32 v[18:19], v[42:43], v[116:117], v[18:19]
	v_cvt_pk_bf16_f32 v16, v16, v17
	v_cvt_pk_bf16_f32 v17, v18, v19
	global_store_dwordx2 v[110:111], v[16:17], off offset:-96
	v_pk_fma_f32 v[16:17], v[72:73], v[36:37], v[130:131] op_sel:[0,0,1] neg_lo:[0,0,1] neg_hi:[0,0,1]
	v_pk_fma_f32 v[18:19], v[74:75], v[124:125], v[130:131] op_sel:[0,0,1] neg_lo:[0,0,1] neg_hi:[0,0,1]
	v_pk_mul_f32 v[16:17], v[16:17], v[2:3] op_sel_hi:[1,0]
	v_pk_mul_f32 v[18:19], v[18:19], v[2:3] op_sel_hi:[1,0]
	v_pk_mul_f32 v[16:17], v[28:29], v[16:17]
	v_pk_mul_f32 v[18:19], v[30:31], v[18:19]
	v_pk_fma_f32 v[16:17], v[44:45], v[128:129], v[16:17]
	v_pk_fma_f32 v[18:19], v[46:47], v[38:39], v[18:19]
	v_cvt_pk_bf16_f32 v16, v16, v17
	v_cvt_pk_bf16_f32 v17, v18, v19
	global_store_dwordx2 v[110:111], v[16:17], off offset:-64
	v_pk_fma_f32 v[16:17], v[76:77], v[24:25], v[130:131] op_sel:[0,0,1] neg_lo:[0,0,1] neg_hi:[0,0,1]
	v_pk_fma_f32 v[18:19], v[78:79], v[26:27], v[130:131] op_sel:[0,0,1] neg_lo:[0,0,1] neg_hi:[0,0,1]
	v_pk_mul_f32 v[16:17], v[16:17], v[2:3] op_sel_hi:[1,0]
	v_pk_mul_f32 v[18:19], v[18:19], v[2:3] op_sel_hi:[1,0]
	v_pk_mul_f32 v[16:17], v[132:133], v[16:17]
	v_pk_mul_f32 v[18:19], v[134:135], v[18:19]
	v_pk_fma_f32 v[16:17], v[136:137], v[150:151], v[16:17]
	v_pk_fma_f32 v[18:19], v[138:139], v[148:149], v[18:19]
	v_pk_fma_f32 v[14:15], v[146:147], v[208:209], v[14:15]
	v_cvt_pk_bf16_f32 v16, v16, v17
	v_cvt_pk_bf16_f32 v17, v18, v19
	v_cvt_pk_bf16_f32 v12, v12, v13
	v_cvt_pk_bf16_f32 v13, v14, v15
	global_store_dwordx2 v[110:111], v[16:17], off offset:-32
	global_store_dwordx2 v[110:111], v[12:13], off
	ds_read_b128 v[12:15], v181
	ds_read_b128 v[16:19], v187
	s_waitcnt lgkmcnt(4)
; #define GAS __attribute__((address_space(1)))
; #define LAS __attribute__((address_space(3)))
; __device__ __forceinline__ f32x4 bf4_to_f32(u32x2 w) { return (f32x4){bflo(w.x), bfhi(w.x), bflo(w.y), bfhi(w.y)}; }
; __device__ __forceinline__ u32x2 f32_to_bf4(f32x4 v) { u32x2 w; w.x = cvtpk(v[0], v[1]); w.y = cvtpk(v[2], v[3]); return w; }
; __device__ __forceinline__ void ml_out_unit(LAS unsigned char* lds, const MixBufs& B, int b, int h, int seg, int tid) {
;     ...
; #pragma unroll
;             for (int vt = 0; vt < 8; ++vt) { const int cl = 16 * vt + 4 * g; const f32x4 xc = bf4_to_f32(*(const LAS u32x2*)(lds + O_XC + (16 * ti + c) * GP128 + cl * 2)), gn = *(const LAS f32x4*)(GN + cl), sk = *(const LAS f32x4*)(SK + cl);
;                 f32x4 r;
; #pragma unroll
;                 for (int i = 0; i < 4; ++i) r[i] = (a1[vt][i] - mu) * rstd * gn[i] + sk[i] * xc[i];
;                 *(GAS u32x2*)(B.A_b + trow * 1024 + h * 128 + cl) = f32_to_bf4(r); }
;             m = mn;
;             __syncthreads();
;         }
	v_lshlrev_b32_e32 v20, 16, v200
	v_and_b32_e32 v21, 0xffff0000, v200
	v_pk_fma_f32 v[22:23], v[86:87], v[94:95], v[130:131] op_sel:[0,0,1] neg_lo:[0,0,1] neg_hi:[0,0,1]
	v_lshl_add_u64 v[64:65], v[64:65], 0, s[4:5]
	v_pk_mul_f32 v[22:23], v[22:23], v[2:3] op_sel_hi:[1,0]
	s_waitcnt lgkmcnt(0)
	v_pk_mul_f32 v[16:17], v[16:17], v[20:21]
	v_pk_fma_f32 v[20:21], v[90:91], v[92:93], v[130:131] op_sel:[0,0,1] neg_lo:[0,0,1] neg_hi:[0,0,1]
	v_pk_fma_f32 v[12:13], v[22:23], v[12:13], v[16:17]
	v_lshlrev_b32_e32 v16, 16, v201
	v_and_b32_e32 v17, 0xffff0000, v201
	v_pk_mul_f32 v[20:21], v[20:21], v[2:3] op_sel_hi:[1,0]
	v_pk_mul_f32 v[16:17], v[18:19], v[16:17]
	v_cvt_pk_bf16_f32 v12, v12, v13
	v_pk_fma_f32 v[14:15], v[20:21], v[14:15], v[16:17]
	v_lshlrev_b32_e32 v20, 16, v204
	v_cvt_pk_bf16_f32 v13, v14, v15
	global_store_dwordx2 v[110:111], v[12:13], off offset:32
	ds_read_b128 v[12:15], v188
	ds_read_b128 v[16:19], v189
	v_and_b32_e32 v21, 0xffff0000, v204
	v_pk_fma_f32 v[22:23], v[84:85], v[96:97], v[130:131] op_sel:[0,0,1] neg_lo:[0,0,1] neg_hi:[0,0,1]
	s_mov_b64 s[4:5], 0x20000
	v_pk_mul_f32 v[22:23], v[22:23], v[2:3] op_sel_hi:[1,0]
	s_waitcnt lgkmcnt(0)
	v_pk_mul_f32 v[16:17], v[16:17], v[20:21]
	v_pk_fma_f32 v[20:21], v[98:99], v[100:101], v[130:131] op_sel:[0,0,1] neg_lo:[0,0,1] neg_hi:[0,0,1]
	v_pk_fma_f32 v[12:13], v[22:23], v[12:13], v[16:17]
	v_lshlrev_b32_e32 v16, 16, v205
	v_and_b32_e32 v17, 0xffff0000, v205
	v_pk_mul_f32 v[20:21], v[20:21], v[2:3] op_sel_hi:[1,0]
	v_pk_mul_f32 v[16:17], v[18:19], v[16:17]
	v_cvt_pk_bf16_f32 v12, v12, v13
	v_pk_fma_f32 v[14:15], v[20:21], v[14:15], v[16:17]
	v_lshlrev_b32_e32 v20, 16, v206
	v_cvt_pk_bf16_f32 v13, v14, v15
	global_store_dwordx2 v[110:111], v[12:13], off offset:64
	ds_read_b128 v[12:15], v190
	ds_read_b128 v[16:19], v191
	v_and_b32_e32 v21, 0xffff0000, v206
	v_pk_fma_f32 v[22:23], v[82:83], v[102:103], v[130:131] op_sel:[0,0,1] neg_lo:[0,0,1] neg_hi:[0,0,1]
	v_lshl_add_u64 v[66:67], v[66:67], 0, s[4:5]
	v_pk_mul_f32 v[22:23], v[22:23], v[2:3] op_sel_hi:[1,0]
	s_waitcnt lgkmcnt(0)
	v_pk_mul_f32 v[16:17], v[16:17], v[20:21]
	v_pk_fma_f32 v[20:21], v[104:105], v[106:107], v[130:131] op_sel:[0,0,1] neg_lo:[0,0,1] neg_hi:[0,0,1]
	v_pk_fma_f32 v[12:13], v[22:23], v[12:13], v[16:17]
	v_lshlrev_b32_e32 v16, 16, v207
	v_and_b32_e32 v17, 0xffff0000, v207
	v_pk_mul_f32 v[20:21], v[20:21], v[2:3] op_sel_hi:[1,0]
	v_pk_mul_f32 v[16:17], v[18:19], v[16:17]
	v_cvt_pk_bf16_f32 v12, v12, v13
	v_pk_fma_f32 v[14:15], v[20:21], v[14:15], v[16:17]
	v_mov_b32_e32 v186, v198
	v_cvt_pk_bf16_f32 v13, v14, v15
	global_store_dwordx2 v[110:111], v[12:13], off offset:96
	s_barrier
	s_cbranch_scc1 .LBB0_678

; #define LAS __attribute__((address_space(3)))
; __device__ __forceinline__ TrItem tr_decode(Frame& F, int r) {
;     TrItem t; t.gain = nullptr; t.scale = 1.f; t.nvalid = 32; t.dst_koff = 0;
;     if (r < P0_I_W1) { t.kb = r / P0_NB1; const int nb = r % P0_NB1; w1_map(nb, t.src_col0, t.nvalid, t.scale); t.W = F.w_in; t.N = DIN; t.WT = F.W1t; t.Kdst = D; t.dst_row0 = 32 * nb; t.gain = F.g_pre_mix; return t; } r -= P0_I_W1;
;     if (r < P0_I_PA) { t.kb = r / (D / 32); const int nb = r % (D / 32); t.W = F.w_pa; t.N = D; t.src_col0 = 32 * nb; t.WT = F.Wpa_t; t.Kdst = 1024; t.dst_row0 = 32 * nb; return t; } r -= P0_I_PA;
;     if (r < P0_I_PB) { t.kb = r / (D / 32); const int nb = r % (D / 32); t.W = F.w_pb; t.N = D; t.src_col0 = 32 * nb; t.WT = F.Wpa_t; t.Kdst = 1024; t.dst_row0 = 32 * nb; t.dst_koff = 512; return t; } r -= P0_I_PB;
;     if (r < P0_I_WO) { t.kb = r / (D / 32); const int nb = r % (D / 32); t.W = F.w_o; t.N = D; t.src_col0 = 32 * nb; t.WT = F.Wo_t; t.Kdst = D; t.dst_row0 = 32 * nb; return t; } r -= P0_I_WO;
;     if (r < P0_I_UP) { t.kb = r / (FF / 32); const int nb = r % (FF / 32); t.W = F.w_up; t.N = FF; t.src_col0 = 32 * nb; t.WT = F.Wup_t; t.Kdst = D; t.dst_row0 = 32 * nb; t.gain = F.g_pre_mlp; return t; } r -= P0_I_UP;
;     { t.kb = r / (D / 32); const int nb = r % (D / 32); t.W = F.w_down; t.N = D; t.src_col0 = 32 * nb; t.WT = F.Wdn_t; t.Kdst = FF; t.dst_row0 = 32 * nb; return t; }
; }
; __device__ __forceinline__ void p0_transposes(Frame& F, int it_lo, int it_hi, int gw, int NGW) {
;     int tx_ = (int)threadIdx.x; asm volatile("" : "+v"(tx_)); const int lane = tx_ & 63;
;     LAS float* scr = (LAS float*)(F.lds + RING_OFF + F.wave * 16384);
;     int it = it_lo + gw; if (it >= it_hi) return;
;     TrItem cur = tr_decode(F, it); f32x4 v[8]; float g[8];
; template <int PH> __device__ __forceinline__ void run_phase(Frame& F, const Args& args) {
;     ...
;             if (F.G == 256 && ((F.vcu >> 4) & 1) == 0) { __syncthreads(); p0_transposes(F, P0_I_W1 + P0_SPLIT, P0_NITEMS, (((F.vcu >> 5) << 4) | (F.vcu & 15)) * NWAVES + F.wave, 128 * NWAVES); }
.LBB0_870:
	v_readlane_b32 s2, v241, 52
	s_bitcmp0_b32 s2, 4
	v_readlane_b32 s4, v241, 46
	s_cselect_b64 s[0:1], -1, 0
	v_readlane_b32 s5, v241, 47
	s_and_b64 s[0:1], s[4:5], s[0:1]
	v_readlane_b32 s68, v241, 42
	v_readlane_b32 s74, v240, 9
	s_and_b64 vcc, exec, s[0:1]
	v_readlane_b32 s66, v240, 13
	v_readlane_b32 s69, v241, 43
	v_readlane_b32 s70, v241, 50
	v_readlane_b32 s72, v240, 11
	v_readlane_b32 s75, v240, 10
	v_readlane_b32 s67, v240, 8
	v_readlane_b32 s76, v240, 7
	v_readlane_b32 s71, v241, 51
	v_readlane_b32 s73, v240, 12
	s_cbranch_vccz .LBB0_1025
	s_lshr_b32 s0, s2, 1
	s_and_b32 s0, s0, 0x1ffffff0
	s_and_b32 s1, s2, 15
	s_or_b32 s0, s0, s1
	s_lshl_b32 s12, s0, 3
	v_readlane_b32 s0, v241, 48
	s_add_i32 s12, s12, s0
	v_mov_b32_e32 v1, v0
	s_addk_i32 s12, 0x800
	s_movk_i32 s101, 0x1980
	s_cmpk_gt_i32 s12, 0x13ff
	s_barrier
	s_cbranch_scc1 .LBB0_1025
.Ltr_entry:
	s_add_i32 s22, s12, 0x980
	s_cmp_gt_i32 s12, -1
	s_cbranch_scc0 .LBB0_878
	s_cmpk_gt_u32 s22, 0xa7f
	s_cbranch_scc0 .LBB0_880
	s_cmpk_gt_u32 s22, 0xb7f
	s_cbranch_scc0 .LBB0_932
	s_cmpk_gt_u32 s22, 0xd7f
	s_cbranch_scc0 .LBB0_933
	s_lshl_b32 s4, s22, 5
	s_cmpk_gt_u32 s22, 0x157f
	s_cbranch_scc0 .LBB0_934
	v_readlane_b32 s36, v241, 18
	s_add_i32 s0, s12, 0xfffff400
	v_readlane_b32 s46, v241, 28
	v_readlane_b32 s47, v241, 29
	s_lshr_b32 s23, s0, 5
	s_and_b32 s24, s4, 0x3e0
	s_mov_b64 s[0:1], 0
	s_mov_b64 s[2:3], 0
	v_readlane_b32 s37, v241, 19
	v_readlane_b32 s38, v241, 20
	v_readlane_b32 s39, v241, 21
	v_readlane_b32 s40, v241, 22
	v_readlane_b32 s41, v241, 23
	v_readlane_b32 s42, v241, 24
	v_readlane_b32 s43, v241, 25
	v_readlane_b32 s44, v241, 26
	v_readlane_b32 s45, v241, 27
	v_readlane_b32 s48, v241, 30
	v_readlane_b32 s49, v241, 31
	v_readlane_b32 s50, v241, 32
	v_readlane_b32 s51, v241, 33
	s_mov_b64 s[6:7], s[46:47]
	s_branch .LBB0_935

; __device__ __forceinline__ TrItem tr_decode(Frame& F, int r) {
;     TrItem t; t.gain = nullptr; t.scale = 1.f; t.nvalid = 32; t.dst_koff = 0;
;     if (r < P0_I_W1) { t.kb = r / P0_NB1; const int nb = r % P0_NB1; w1_map(nb, t.src_col0, t.nvalid, t.scale); t.W = F.w_in; t.N = DIN; t.WT = F.W1t; t.Kdst = D; t.dst_row0 = 32 * nb; t.gain = F.g_pre_mix; return t; } r -= P0_I_W1;
;     if (r < P0_I_PA) { t.kb = r / (D / 32); const int nb = r % (D / 32); t.W = F.w_pa; t.N = D; t.src_col0 = 32 * nb; t.WT = F.Wpa_t; t.Kdst = 1024; t.dst_row0 = 32 * nb; return t; } r -= P0_I_PA;
;     if (r < P0_I_PB) { t.kb = r / (D / 32); const int nb = r % (D / 32); t.W = F.w_pb; t.N = D; t.src_col0 = 32 * nb; t.WT = F.Wpa_t; t.Kdst = 1024; t.dst_row0 = 32 * nb; t.dst_koff = 512; return t; } r -= P0_I_PB;
;     if (r < P0_I_WO) { t.kb = r / (D / 32); const int nb = r % (D / 32); t.W = F.w_o; t.N = D; t.src_col0 = 32 * nb; t.WT = F.Wo_t; t.Kdst = D; t.dst_row0 = 32 * nb; return t; } r -= P0_I_WO;
;     if (r < P0_I_UP) { t.kb = r / (FF / 32); const int nb = r % (FF / 32); t.W = F.w_up; t.N = FF; t.src_col0 = 32 * nb; t.WT = F.Wup_t; t.Kdst = D; t.dst_row0 = 32 * nb; t.gain = F.g_pre_mlp; return t; } r -= P0_I_UP;
;     { t.kb = r / (D / 32); const int nb = r % (D / 32); t.W = F.w_down; t.N = D; t.src_col0 = 32 * nb; t.WT = F.Wdn_t; t.Kdst = FF; t.dst_row0 = 32 * nb; return t; }
; __device__ __forceinline__ void p0_transposes(Frame& F, int it_lo, int it_hi, int gw, int NGW) {
;     ...
;         const int nx = it + NGW; const bool more = nx < it_hi;
;         TrItem nxt = cur; f32x4 v2[8]; float g2[8];
;         if (more) { nxt = tr_decode(F, nx); tr_load(nxt, v2, g2, lane); }
.LBB0_975:
	s_add_i32 s29, s22, 0x400
	s_cmp_lt_i32 s22, s101
	s_cselect_b64 s[8:9], -1, 0
	s_cmp_ge_i32 s22, s101
	s_cselect_b64 s[6:7], -1, 0
	s_and_b64 vcc, exec, s[6:7]
	s_cbranch_vccnz .LBB0_983
	s_cmpk_gt_i32 s22, 0x57f
	s_mov_b64 s[16:17], -1
	s_cbranch_scc0 .LBB0_993
	s_cmpk_gt_u32 s29, 0xa7f
	s_cbranch_scc0 .LBB0_984
	s_cmpk_gt_u32 s29, 0xb7f
	s_cbranch_scc0 .LBB0_985
	s_cmpk_gt_u32 s29, 0xd7f
	s_cbranch_scc0 .LBB0_986
	s_lshl_b32 s14, s29, 5
	s_cmpk_gt_u32 s29, 0x157f
	s_cbranch_scc0 .LBB0_1023
	v_readlane_b32 s36, v241, 18
	s_add_i32 s2, s22, 0xffffee80
	v_readlane_b32 s46, v241, 28
	v_readlane_b32 s47, v241, 29
	s_lshr_b32 s30, s2, 5
	s_and_b32 s31, s14, 0x3e0
	s_mov_b64 s[2:3], 0
	v_readlane_b32 s37, v241, 19
	v_readlane_b32 s38, v241, 20
	v_readlane_b32 s39, v241, 21
	v_readlane_b32 s40, v241, 22
	v_readlane_b32 s41, v241, 23
	v_readlane_b32 s42, v241, 24
	v_readlane_b32 s43, v241, 25
	v_readlane_b32 s44, v241, 26
	v_readlane_b32 s45, v241, 27
	v_readlane_b32 s48, v241, 30
	v_readlane_b32 s49, v241, 31
	v_readlane_b32 s50, v241, 32
	v_readlane_b32 s51, v241, 33
	s_mov_b64 s[12:13], s[46:47]
	s_cbranch_execz .LBB0_1024
	s_movk_i32 s33, 0x1000
	s_mov_b64 s[14:15], 0x400
	s_mov_b64 s[10:11], s[68:69]
	s_cbranch_execz .LBB0_987
	s_branch .LBB0_988

; __device__ __forceinline__ unsigned xb_ld(unsigned* p)              { return __hip_atomic_load(p, __ATOMIC_RELAXED, __HIP_MEMORY_SCOPE_AGENT); }
; __device__ __forceinline__ void xcd_barrier_complete(unsigned* bar, unsigned x, unsigned& nloc, unsigned& nx) {
;     const unsigned G = gridDim.x * gridDim.y * gridDim.z;
;     unsigned sum, cnt, mine, sp = 0u;
;     for (;;) {
;         sum = 0u; cnt = 0u; mine = 0u;
; #pragma unroll
;         for (unsigned j = 0; j < 16; ++j) { const unsigned c = xb_ld(&bar[XB_XCNT(j)]); sum += c; cnt += (c > 0u) ? 1u : 0u; mine = (j == x) ? c : mine; }
;         if (sum == G) break;
;         __builtin_amdgcn_s_sleep(1);
;         if ((++sp & 255u) == 0u) { if (xb_ld(&bar[XB_TMO])) break; if (sp > XB_SPIN_CAP) { atomicAdd(&bar[XB_TMO], 1u); break; } }
;     }
;     nloc = mine > 0u ? mine : 1u; nx = cnt > 0u ? cnt : 1u;
; }
; __device__ __forceinline__ void xcd_barrier(const XcdBarrier& b) {
;     asm volatile("s_waitcnt vmcnt(0)" ::: "memory");
;     __syncthreads();
;     if (threadIdx.x == 0) {
;         unsigned* bar = b.bar;
;         __builtin_amdgcn_s_waitcnt(0);
;         unsigned nloc = b.st[0], nx = b.st[1];
;         if (nloc == 0u) { xcd_barrier_complete(bar, b.x, nloc, nx); b.st[0] = nloc; b.st[1] = nx; }
.LBB0_1025:
	s_bitcmp1_b32 s99, 0
	s_cbranch_scc1 .Lp1_ret
	s_waitcnt vmcnt(0)
	s_barrier
	s_mov_b64 s[0:1], exec
	v_readlane_b32 s2, v241, 34
	v_readlane_b32 s3, v241, 35
	s_and_b64 s[2:3], s[0:1], s[2:3]
	s_mov_b64 exec, s[2:3]
	s_cbranch_execz .LBB0_1077
	s_add_i32 s2, 0, 0x27f60
	v_mov_b32_e32 v1, s2
	s_waitcnt vmcnt(0) expcnt(0) lgkmcnt(0)
	ds_read_b32 v3, v1
	s_add_i32 s2, 0, 0x27f64
	v_mov_b32_e32 v1, s2
	ds_read_b32 v1, v1
	s_waitcnt lgkmcnt(1)
	v_cmp_ne_u32_e32 vcc, 0, v3
	s_cbranch_vccnz .LBB0_1041
	v_readlane_b32 s2, v241, 0
	v_readlane_b32 s3, v241, 1
	s_load_dwordx2 s[6:7], s[2:3], 0x4
	s_add_u32 s2, s88, 0x4200
	s_addc_u32 s3, s89, 0
	s_add_u32 s4, s88, 0x4400
	s_addc_u32 s5, s89, 0
	s_waitcnt lgkmcnt(0)
	s_mul_i32 s30, s6, s76
	s_add_u32 s6, s88, 0x4500
	s_mul_i32 s30, s30, s7
	s_addc_u32 s7, s89, 0
	s_add_u32 s8, s88, 0x4600
	s_addc_u32 s9, s89, 0
	s_add_u32 s10, s88, 0x4700
	s_addc_u32 s11, s89, 0
	s_add_u32 s12, s88, 0x4800
	s_addc_u32 s13, s89, 0
	s_add_u32 s14, s88, 0x4900
	s_addc_u32 s15, s89, 0
	s_add_u32 s16, s88, 0x4a00
	s_addc_u32 s17, s89, 0
	s_add_u32 s18, s88, 0x4b00
	s_addc_u32 s19, s89, 0
	s_add_u32 s20, s88, 0x4c00
	s_addc_u32 s21, s89, 0
	s_add_u32 s22, s88, 0x4d00
	s_addc_u32 s23, s89, 0
	s_add_u32 s24, s88, 0x4e00
	s_addc_u32 s25, s89, 0
	s_add_u32 s26, s88, 0x4f00
	s_addc_u32 s27, s89, 0
	s_add_u32 s28, s88, 0x5000
	s_addc_u32 s29, s89, 0
	s_add_u32 s34, s88, 0x5100
	s_addc_u32 s35, s89, 0
	s_add_u32 s36, s88, 0x5200
	s_addc_u32 s37, s89, 0
	s_add_u32 s38, s88, 0x5300
	s_addc_u32 s39, s89, 0
	s_mov_b32 s31, 1
	v_mov_b32_e32 v17, 0
	s_branch .LBB0_1029

; __global__ void __launch_bounds__(NWAVES * 64, 2) skel_fwd(Args args) {
	.amdhsa_kernel _Z8skel_fwd4Args
		.amdhsa_group_segment_fixed_size 0
		.amdhsa_private_segment_fixed_size 0
		.amdhsa_kernarg_size 456
		.amdhsa_user_sgpr_count 2
		.amdhsa_user_sgpr_dispatch_ptr 0
		.amdhsa_user_sgpr_queue_ptr 0
		.amdhsa_user_sgpr_kernarg_segment_ptr 1
		.amdhsa_user_sgpr_dispatch_id 0
		.amdhsa_user_sgpr_kernarg_preload_length 0
		.amdhsa_user_sgpr_kernarg_preload_offset 0
		.amdhsa_user_sgpr_private_segment_size 0
		.amdhsa_uses_dynamic_stack 0
		.amdhsa_enable_private_segment 0
		.amdhsa_system_sgpr_workgroup_id_x 1
		.amdhsa_system_sgpr_workgroup_id_y 0
		.amdhsa_system_sgpr_workgroup_id_z 0
		.amdhsa_system_sgpr_workgroup_info 0
		.amdhsa_system_vgpr_workitem_id 0
		.amdhsa_next_free_vgpr 256
		.amdhsa_next_free_sgpr 102
		.amdhsa_accum_offset 256
		.amdhsa_reserve_vcc 1
		.amdhsa_float_round_mode_32 0
		.amdhsa_float_round_mode_16_64 0
		.amdhsa_float_denorm_mode_32 3
		.amdhsa_float_denorm_mode_16_64 3
		.amdhsa_dx10_clamp 1
		.amdhsa_ieee_mode 1
		.amdhsa_fp16_overflow 0
		.amdhsa_tg_split 0
		.amdhsa_exception_fp_ieee_invalid_op 0
		.amdhsa_exception_fp_denorm_src 0
		.amdhsa_exception_fp_ieee_div_zero 0
		.amdhsa_exception_fp_ieee_overflow 0
		.amdhsa_exception_fp_ieee_underflow 0
		.amdhsa_exception_fp_ieee_inexact 0
		.amdhsa_exception_int_div_zero 0
	.end_amdhsa_kernel

; __global__ void __launch_bounds__(NWAVES * 64, 2) skel_fwd(Args args) {
amdhsa.kernels:
  - .agpr_count:     0
    .args:
      - .offset:         0
        .size:           200
        .value_kind:     by_value
      - .offset:         200
        .size:           4
        .value_kind:     hidden_block_count_x
      - .offset:         204
        .size:           4
        .value_kind:     hidden_block_count_y
      - .offset:         208
        .size:           4
        .value_kind:     hidden_block_count_z
      - .offset:         212
        .size:           2
        .value_kind:     hidden_group_size_x
      - .offset:         214
        .size:           2
        .value_kind:     hidden_group_size_y
      - .offset:         216
        .size:           2
        .value_kind:     hidden_group_size_z
      - .offset:         218
        .size:           2
        .value_kind:     hidden_remainder_x
      - .offset:         220
        .size:           2
        .value_kind:     hidden_remainder_y
      - .offset:         222
        .size:           2
        .value_kind:     hidden_remainder_z
      - .offset:         240
        .size:           8
        .value_kind:     hidden_global_offset_x
      - .offset:         248
        .size:           8
        .value_kind:     hidden_global_offset_y
      - .offset:         256
        .size:           8
        .value_kind:     hidden_global_offset_z
      - .offset:         264
        .size:           2
        .value_kind:     hidden_grid_dims
      - .offset:         320
        .size:           4
        .value_kind:     hidden_dynamic_lds_size
    .group_segment_fixed_size: 0
    .kernarg_segment_align: 8
    .kernarg_segment_size: 456
    .language:       OpenCL C
    .language_version:
      - 2
      - 0
    .max_flat_workgroup_size: 512
    .name:           _Z8skel_fwd4Args
    .private_segment_fixed_size: 0
    .sgpr_count:     108
    .sgpr_spill_count: 85
    .symbol:         _Z8skel_fwd4Args.kd
    .uniform_work_group_size: 1
    .uses_dynamic_stack: false
    .vgpr_count:     256
    .vgpr_spill_count: 0
    .wavefront_size: 64
